# saddr form for K-loop LDS-DMA loads in 9 of 10 GEMM loops (removes 16 v_lshl_add_u64 per iteration)
# speedup vs baseline: 1.0086x; 1.0086x over previous
.LBB0_170:
	ds_read_b128 v[136:139], v191
	ds_read_b128 v[158:161], v191 offset:1024
	ds_read_b128 v[162:165], v191 offset:2048
	ds_read_b128 v[166:169], v191 offset:3072
	ds_read_b128 v[170:173], v192
	ds_read_b128 v[174:177], v192 offset:1024
	ds_read_b128 v[178:181], v192 offset:2048
	ds_read_b128 v[194:197], v192 offset:3072
	s_add_u32 s0, s42, 0xfff00080
	s_addc_u32 s50, s43, -1
	s_cmp_eq_u32 s70, 60
	s_cselect_b32 s53, s23, s50
	s_cselect_b32 s52, s41, s0
	s_cselect_b32 s51, s21, s68
	s_cselect_b32 s50, s66, s67
	s_add_i32 m0, s31, 0xc000
	ds_read_b128 v[198:201], v193
	ds_read_b128 v[202:205], v193 offset:1024
	ds_read_b128 v[206:209], v193 offset:2048
	ds_read_b128 v[210:213], v193 offset:3072
	ds_read_b128 v[214:217], v193 offset:4096
	ds_read_b128 v[218:221], v193 offset:5120
	ds_read_b128 v[222:225], v193 offset:6144
	ds_read_b128 v[226:229], v193 offset:7168
	global_load_lds_dwordx4 v152, s[42:43]
	s_add_i32 m0, s31, 0xe000
	s_nop 0
	global_load_lds_dwordx4 v154, s[42:43]
	s_waitcnt vmcnt(8)
	s_waitcnt lgkmcnt(0)
	s_barrier
	s_setprio 1
	s_waitcnt lgkmcnt(0)
	v_mfma_f32_16x16x32_bf16 v[132:135], v[136:139], v[198:201], v[132:135]
	v_mfma_f32_16x16x32_bf16 v[128:131], v[162:165], v[198:201], v[128:131]
	v_mfma_f32_16x16x32_bf16 v[116:119], v[136:139], v[206:209], v[116:119]
	v_mfma_f32_16x16x32_bf16 v[112:115], v[162:165], v[206:209], v[112:115]
	v_mfma_f32_16x16x32_bf16 v[100:103], v[136:139], v[214:217], v[100:103]
	v_mfma_f32_16x16x32_bf16 v[96:99], v[162:165], v[214:217], v[96:99]
	v_mfma_f32_16x16x32_bf16 v[84:87], v[136:139], v[222:225], v[84:87]
	v_mfma_f32_16x16x32_bf16 v[80:83], v[162:165], v[222:225], v[80:83]
	v_mfma_f32_16x16x32_bf16 v[132:135], v[158:161], v[202:205], v[132:135]
	v_mfma_f32_16x16x32_bf16 v[128:131], v[166:169], v[202:205], v[128:131]
	v_mfma_f32_16x16x32_bf16 v[116:119], v[158:161], v[210:213], v[116:119]
	v_mfma_f32_16x16x32_bf16 v[112:115], v[166:169], v[210:213], v[112:115]
	v_mfma_f32_16x16x32_bf16 v[100:103], v[158:161], v[218:221], v[100:103]
	v_mfma_f32_16x16x32_bf16 v[96:99], v[166:169], v[218:221], v[96:99]
	v_mfma_f32_16x16x32_bf16 v[84:87], v[158:161], v[226:229], v[84:87]
	v_mfma_f32_16x16x32_bf16 v[80:83], v[166:169], v[226:229], v[80:83]
	s_setprio 0
	s_setprio 1
	v_mfma_f32_16x16x32_bf16 v[124:127], v[170:173], v[198:201], v[124:127]
	v_mfma_f32_16x16x32_bf16 v[120:123], v[178:181], v[198:201], v[120:123]
	v_mfma_f32_16x16x32_bf16 v[108:111], v[170:173], v[206:209], v[108:111]
	v_mfma_f32_16x16x32_bf16 v[104:107], v[178:181], v[206:209], v[104:107]
	v_mfma_f32_16x16x32_bf16 v[92:95], v[170:173], v[214:217], v[92:95]
	v_mfma_f32_16x16x32_bf16 v[88:91], v[178:181], v[214:217], v[88:91]
	v_mfma_f32_16x16x32_bf16 v[76:79], v[170:173], v[222:225], v[76:79]
	v_mfma_f32_16x16x32_bf16 v[72:75], v[178:181], v[222:225], v[72:75]
	v_mfma_f32_16x16x32_bf16 v[124:127], v[174:177], v[202:205], v[124:127]
	v_mfma_f32_16x16x32_bf16 v[120:123], v[194:197], v[202:205], v[120:123]
	v_mfma_f32_16x16x32_bf16 v[108:111], v[174:177], v[210:213], v[108:111]
	v_mfma_f32_16x16x32_bf16 v[104:107], v[194:197], v[210:213], v[104:107]
	v_mfma_f32_16x16x32_bf16 v[92:95], v[174:177], v[218:221], v[92:95]
	v_mfma_f32_16x16x32_bf16 v[88:91], v[194:197], v[218:221], v[88:91]
	v_mfma_f32_16x16x32_bf16 v[76:79], v[174:177], v[226:229], v[76:79]
	v_mfma_f32_16x16x32_bf16 v[72:75], v[194:197], v[226:229], v[72:75]
	s_setprio 0
	s_barrier
	s_add_i32 s0, s61, s19
	s_mov_b32 m0, s0
	ds_read_b128 v[198:201], v193 offset:16384
	ds_read_b128 v[202:205], v193 offset:17408
	ds_read_b128 v[206:209], v193 offset:18432
	ds_read_b128 v[210:213], v193 offset:19456
	ds_read_b128 v[214:217], v193 offset:20480
	ds_read_b128 v[218:221], v193 offset:21504
	ds_read_b128 v[222:225], v193 offset:22528
	ds_read_b128 v[226:229], v193 offset:23552
	global_load_lds_dwordx4 v142, s[50:51]
	s_add_i32 m0, s0, 0x2000
	s_add_u32 s72, s50, 0x100000
	s_addc_u32 s73, s51, 0
	s_add_i32 s0, s62, s19
	global_load_lds_dwordx4 v146, s[50:51]
	s_mov_b32 m0, s0
	s_nop 0
	global_load_lds_dwordx4 v142, s[72:73]
	s_add_i32 m0, s0, 0x2000
	s_nop 0
	global_load_lds_dwordx4 v146, s[72:73]
	s_mov_b32 m0, s31
	s_nop 0
	global_load_lds_dwordx4 v140, s[52:53]
	s_mov_b32 m0, s35
	s_nop 0
	global_load_lds_dwordx4 v144, s[52:53]
	s_waitcnt vmcnt(8)
	s_waitcnt lgkmcnt(0)
	s_barrier
	s_setprio 1
	s_waitcnt lgkmcnt(0)
	v_mfma_f32_16x16x32_bf16 v[68:71], v[136:139], v[198:201], v[68:71]
	v_mfma_f32_16x16x32_bf16 v[64:67], v[162:165], v[198:201], v[64:67]
	v_mfma_f32_16x16x32_bf16 v[52:55], v[136:139], v[206:209], v[52:55]
	v_mfma_f32_16x16x32_bf16 v[48:51], v[162:165], v[206:209], v[48:51]
	v_mfma_f32_16x16x32_bf16 v[36:39], v[136:139], v[214:217], v[36:39]
	v_mfma_f32_16x16x32_bf16 v[32:35], v[162:165], v[214:217], v[32:35]
	v_mfma_f32_16x16x32_bf16 v[20:23], v[136:139], v[222:225], v[20:23]
	v_mfma_f32_16x16x32_bf16 v[16:19], v[162:165], v[222:225], v[16:19]
	v_mfma_f32_16x16x32_bf16 v[68:71], v[158:161], v[202:205], v[68:71]
	v_mfma_f32_16x16x32_bf16 v[64:67], v[166:169], v[202:205], v[64:67]
	v_mfma_f32_16x16x32_bf16 v[52:55], v[158:161], v[210:213], v[52:55]
	v_mfma_f32_16x16x32_bf16 v[48:51], v[166:169], v[210:213], v[48:51]
	v_mfma_f32_16x16x32_bf16 v[36:39], v[158:161], v[218:221], v[36:39]
	v_mfma_f32_16x16x32_bf16 v[32:35], v[166:169], v[218:221], v[32:35]
	v_mfma_f32_16x16x32_bf16 v[20:23], v[158:161], v[226:229], v[20:23]
	v_mfma_f32_16x16x32_bf16 v[16:19], v[166:169], v[226:229], v[16:19]
	s_setprio 0
	s_setprio 1
	v_mfma_f32_16x16x32_bf16 v[60:63], v[170:173], v[198:201], v[60:63]
	v_mfma_f32_16x16x32_bf16 v[56:59], v[178:181], v[198:201], v[56:59]
	v_mfma_f32_16x16x32_bf16 v[44:47], v[170:173], v[206:209], v[44:47]
	v_mfma_f32_16x16x32_bf16 v[40:43], v[178:181], v[206:209], v[40:43]
	v_mfma_f32_16x16x32_bf16 v[28:31], v[170:173], v[214:217], v[28:31]
	v_mfma_f32_16x16x32_bf16 v[24:27], v[178:181], v[214:217], v[24:27]
	v_mfma_f32_16x16x32_bf16 v[12:15], v[170:173], v[222:225], v[12:15]
	v_mfma_f32_16x16x32_bf16 v[6:9], v[178:181], v[222:225], v[8:11]
	v_mfma_f32_16x16x32_bf16 v[60:63], v[174:177], v[202:205], v[60:63]
	v_mfma_f32_16x16x32_bf16 v[56:59], v[194:197], v[202:205], v[56:59]
	v_mfma_f32_16x16x32_bf16 v[44:47], v[174:177], v[210:213], v[44:47]
	v_mfma_f32_16x16x32_bf16 v[40:43], v[194:197], v[210:213], v[40:43]
	v_mfma_f32_16x16x32_bf16 v[28:31], v[174:177], v[218:221], v[28:31]
	v_mfma_f32_16x16x32_bf16 v[24:27], v[194:197], v[218:221], v[24:27]
	v_mfma_f32_16x16x32_bf16 v[12:15], v[174:177], v[226:229], v[12:15]
	v_mfma_f32_16x16x32_bf16 v[6:9], v[194:197], v[226:229], v[6:9]
	s_setprio 0
	s_barrier
	s_add_i32 s0, 0, 0x18000
	v_add_u32_e32 v5, s0, v1
	s_add_i32 s71, 0, 0x1c000
	ds_read_b128 v[136:139], v5
	ds_read_b128 v[158:161], v5 offset:1024
	ds_read_b128 v[162:165], v5 offset:2048
	ds_read_b128 v[166:169], v5 offset:3072
	v_add_u32_e32 v5, s71, v1
	ds_read_b128 v[170:173], v5
	ds_read_b128 v[174:177], v5 offset:1024
	ds_read_b128 v[178:181], v5 offset:2048
	ds_read_b128 v[194:197], v5 offset:3072
	s_add_u32 s98, s52, 0x100000
	s_addc_u32 s99, s53, 0
	s_mov_b32 m0, s45
	ds_read_b128 v[198:201], v193 offset:32768
	ds_read_b128 v[202:205], v193 offset:33792
	ds_read_b128 v[206:209], v193 offset:34816
	ds_read_b128 v[210:213], v193 offset:35840
	ds_read_b128 v[214:217], v193 offset:36864
	ds_read_b128 v[218:221], v193 offset:37888
	ds_read_b128 v[222:225], v193 offset:38912
	ds_read_b128 v[226:229], v193 offset:39936
	global_load_lds_dwordx4 v140, s[98:99]
	s_mov_b32 m0, s46
	s_nop 0
	global_load_lds_dwordx4 v144, s[98:99]
	s_waitcnt vmcnt(8)
	s_waitcnt lgkmcnt(0)
	s_barrier
	s_setprio 1
	s_waitcnt lgkmcnt(0)
	v_mfma_f32_16x16x32_bf16 v[132:135], v[136:139], v[198:201], v[132:135]
	v_mfma_f32_16x16x32_bf16 v[128:131], v[162:165], v[198:201], v[128:131]
	v_mfma_f32_16x16x32_bf16 v[116:119], v[136:139], v[206:209], v[116:119]
	v_mfma_f32_16x16x32_bf16 v[112:115], v[162:165], v[206:209], v[112:115]
	v_mfma_f32_16x16x32_bf16 v[100:103], v[136:139], v[214:217], v[100:103]
	v_mfma_f32_16x16x32_bf16 v[96:99], v[162:165], v[214:217], v[96:99]
	v_mfma_f32_16x16x32_bf16 v[84:87], v[136:139], v[222:225], v[84:87]
	v_mfma_f32_16x16x32_bf16 v[80:83], v[162:165], v[222:225], v[80:83]
	v_mfma_f32_16x16x32_bf16 v[132:135], v[158:161], v[202:205], v[132:135]
	v_mfma_f32_16x16x32_bf16 v[128:131], v[166:169], v[202:205], v[128:131]
	v_mfma_f32_16x16x32_bf16 v[116:119], v[158:161], v[210:213], v[116:119]
	v_mfma_f32_16x16x32_bf16 v[112:115], v[166:169], v[210:213], v[112:115]
	v_mfma_f32_16x16x32_bf16 v[100:103], v[158:161], v[218:221], v[100:103]
	v_mfma_f32_16x16x32_bf16 v[96:99], v[166:169], v[218:221], v[96:99]
	v_mfma_f32_16x16x32_bf16 v[84:87], v[158:161], v[226:229], v[84:87]
	v_mfma_f32_16x16x32_bf16 v[80:83], v[166:169], v[226:229], v[80:83]
	s_setprio 0
	s_setprio 1
	v_mfma_f32_16x16x32_bf16 v[124:127], v[170:173], v[198:201], v[124:127]
	v_mfma_f32_16x16x32_bf16 v[120:123], v[178:181], v[198:201], v[120:123]
	v_mfma_f32_16x16x32_bf16 v[108:111], v[170:173], v[206:209], v[108:111]
	v_mfma_f32_16x16x32_bf16 v[104:107], v[178:181], v[206:209], v[104:107]
	v_mfma_f32_16x16x32_bf16 v[92:95], v[170:173], v[214:217], v[92:95]
	v_mfma_f32_16x16x32_bf16 v[88:91], v[178:181], v[214:217], v[88:91]
	v_mfma_f32_16x16x32_bf16 v[76:79], v[170:173], v[222:225], v[76:79]
	v_mfma_f32_16x16x32_bf16 v[72:75], v[178:181], v[222:225], v[72:75]
	v_mfma_f32_16x16x32_bf16 v[124:127], v[174:177], v[202:205], v[124:127]
	v_mfma_f32_16x16x32_bf16 v[120:123], v[194:197], v[202:205], v[120:123]
	v_mfma_f32_16x16x32_bf16 v[108:111], v[174:177], v[210:213], v[108:111]
	v_mfma_f32_16x16x32_bf16 v[104:107], v[194:197], v[210:213], v[104:107]
	v_mfma_f32_16x16x32_bf16 v[92:95], v[174:177], v[218:221], v[92:95]
	v_mfma_f32_16x16x32_bf16 v[88:91], v[194:197], v[218:221], v[88:91]
	v_mfma_f32_16x16x32_bf16 v[76:79], v[174:177], v[226:229], v[76:79]
	v_mfma_f32_16x16x32_bf16 v[72:75], v[194:197], v[226:229], v[72:75]
	s_setprio 0
	s_barrier
	s_add_i32 s0, s0, s19
	s_add_i32 m0, s0, 0xffffff80
	ds_read_b128 v[198:201], v193 offset:49152
	ds_read_b128 v[202:205], v193 offset:50176
	ds_read_b128 v[206:209], v193 offset:51200
	ds_read_b128 v[210:213], v193 offset:52224
	ds_read_b128 v[214:217], v193 offset:53248
	ds_read_b128 v[218:221], v193 offset:54272
	ds_read_b128 v[222:225], v193 offset:55296
	ds_read_b128 v[226:229], v193 offset:56320
	global_load_lds_dwordx4 v142, s[50:51] offset:128
	s_add_i32 m0, s0, 0x1f80
	s_add_i32 s0, s71, s19
	global_load_lds_dwordx4 v146, s[50:51] offset:128
	s_add_u32 s50, s50, 0x100080
	s_addc_u32 s51, s51, 0
	s_mov_b32 m0, s0
	s_nop 0
	global_load_lds_dwordx4 v142, s[50:51]
	s_add_i32 m0, s0, 0x2000
	s_nop 0
	global_load_lds_dwordx4 v146, s[50:51]
	s_add_i32 m0, s56, 0xffffff80
	s_nop 0
	global_load_lds_dwordx4 v140, s[52:53] offset:128
	s_add_i32 m0, s57, 0xffffff80
	s_nop 0
	global_load_lds_dwordx4 v144, s[52:53] offset:128
	s_waitcnt vmcnt(8)
	s_waitcnt lgkmcnt(0)
	s_barrier
	s_setprio 1
	s_waitcnt lgkmcnt(0)
	v_mfma_f32_16x16x32_bf16 v[68:71], v[136:139], v[198:201], v[68:71]
	v_mfma_f32_16x16x32_bf16 v[64:67], v[162:165], v[198:201], v[64:67]
	v_mfma_f32_16x16x32_bf16 v[52:55], v[136:139], v[206:209], v[52:55]
	v_mfma_f32_16x16x32_bf16 v[48:51], v[162:165], v[206:209], v[48:51]
	v_mfma_f32_16x16x32_bf16 v[36:39], v[136:139], v[214:217], v[36:39]
	v_mfma_f32_16x16x32_bf16 v[32:35], v[162:165], v[214:217], v[32:35]
	v_mfma_f32_16x16x32_bf16 v[20:23], v[136:139], v[222:225], v[20:23]
	v_mfma_f32_16x16x32_bf16 v[16:19], v[162:165], v[222:225], v[16:19]
	v_mfma_f32_16x16x32_bf16 v[68:71], v[158:161], v[202:205], v[68:71]
	v_mfma_f32_16x16x32_bf16 v[64:67], v[166:169], v[202:205], v[64:67]
	v_mfma_f32_16x16x32_bf16 v[52:55], v[158:161], v[210:213], v[52:55]
	v_mfma_f32_16x16x32_bf16 v[48:51], v[166:169], v[210:213], v[48:51]
	v_mfma_f32_16x16x32_bf16 v[36:39], v[158:161], v[218:221], v[36:39]
	v_mfma_f32_16x16x32_bf16 v[32:35], v[166:169], v[218:221], v[32:35]
	v_mfma_f32_16x16x32_bf16 v[20:23], v[158:161], v[226:229], v[20:23]
	v_mfma_f32_16x16x32_bf16 v[16:19], v[166:169], v[226:229], v[16:19]
	s_setprio 0
	s_setprio 1
	v_mfma_f32_16x16x32_bf16 v[60:63], v[170:173], v[198:201], v[60:63]
	v_mfma_f32_16x16x32_bf16 v[56:59], v[178:181], v[198:201], v[56:59]
	v_mfma_f32_16x16x32_bf16 v[44:47], v[170:173], v[206:209], v[44:47]
	v_mfma_f32_16x16x32_bf16 v[40:43], v[178:181], v[206:209], v[40:43]
	v_mfma_f32_16x16x32_bf16 v[28:31], v[170:173], v[214:217], v[28:31]
	v_mfma_f32_16x16x32_bf16 v[24:27], v[178:181], v[214:217], v[24:27]
	v_mfma_f32_16x16x32_bf16 v[10:13], v[170:173], v[222:225], v[12:15]
	v_mfma_f32_16x16x32_bf16 v[6:9], v[178:181], v[222:225], v[6:9]
	v_mfma_f32_16x16x32_bf16 v[60:63], v[174:177], v[202:205], v[60:63]
	v_mfma_f32_16x16x32_bf16 v[56:59], v[194:197], v[202:205], v[56:59]
	v_mfma_f32_16x16x32_bf16 v[44:47], v[174:177], v[210:213], v[44:47]
	v_mfma_f32_16x16x32_bf16 v[40:43], v[194:197], v[210:213], v[40:43]
	v_mfma_f32_16x16x32_bf16 v[28:31], v[174:177], v[218:221], v[28:31]
	v_mfma_f32_16x16x32_bf16 v[24:27], v[194:197], v[218:221], v[24:27]
	v_mfma_f32_16x16x32_bf16 v[12:15], v[174:177], v[226:229], v[10:13]
	v_mfma_f32_16x16x32_bf16 v[8:11], v[194:197], v[226:229], v[6:9]
	s_setprio 0
	s_barrier
	s_add_i32 s70, s70, 2
	s_add_u32 s42, s42, 0x100
	s_addc_u32 s43, s43, 0
	s_add_u32 s67, s67, 0x100
	s_addc_u32 s68, s68, 0
	s_cmp_gt_u32 s70, 61
	s_cbranch_scc0 .LBB0_170
	s_and_b64 vcc, exec, s[16:17]
	s_cbranch_vccz .LBB0_173
	s_barrier

.LBB0_342:
	ds_read_b128 v[132:135], v209
	ds_read_b128 v[136:139], v209 offset:1024
	ds_read_b128 v[140:143], v209 offset:2048
	ds_read_b128 v[144:147], v209 offset:3072
	ds_read_b128 v[148:151], v210
	ds_read_b128 v[152:155], v210 offset:1024
	ds_read_b128 v[156:159], v210 offset:2048
	ds_read_b128 v[160:163], v210 offset:3072
	s_add_u32 s0, s26, 0xffd50080
	s_addc_u32 s28, s27, -1
	s_cmpk_eq_i32 s62, 0xa8
	s_cselect_b32 s31, s7, s28
	s_cselect_b32 s30, s6, s0
	s_cselect_b32 s29, s25, s61
	s_cselect_b32 s28, s24, s60
	s_add_i32 m0, s43, 0xc000
	ds_read_b128 v[164:167], v211
	ds_read_b128 v[168:171], v211 offset:1024
	ds_read_b128 v[172:175], v211 offset:2048
	ds_read_b128 v[176:179], v211 offset:3072
	ds_read_b128 v[196:199], v211 offset:4096
	ds_read_b128 v[200:203], v211 offset:5120
	ds_read_b128 v[204:207], v211 offset:6144
	ds_read_b128 v[214:217], v211 offset:7168
	global_load_lds_dwordx4 v188, s[26:27]
	s_add_i32 m0, s43, 0xe000
	s_nop 0
	global_load_lds_dwordx4 v190, s[26:27]
	s_waitcnt vmcnt(8)
	s_waitcnt lgkmcnt(0)
	s_barrier
	s_setprio 1
	s_waitcnt lgkmcnt(0)
	v_mfma_f32_16x16x32_bf16 v[128:131], v[132:135], v[164:167], v[128:131]
	v_mfma_f32_16x16x32_bf16 v[124:127], v[140:143], v[164:167], v[124:127]
	v_mfma_f32_16x16x32_bf16 v[112:115], v[132:135], v[172:175], v[112:115]
	v_mfma_f32_16x16x32_bf16 v[108:111], v[140:143], v[172:175], v[108:111]
	v_mfma_f32_16x16x32_bf16 v[96:99], v[132:135], v[196:199], v[96:99]
	v_mfma_f32_16x16x32_bf16 v[92:95], v[140:143], v[196:199], v[92:95]
	v_mfma_f32_16x16x32_bf16 v[80:83], v[132:135], v[204:207], v[80:83]
	v_mfma_f32_16x16x32_bf16 v[76:79], v[140:143], v[204:207], v[76:79]
	v_mfma_f32_16x16x32_bf16 v[128:131], v[136:139], v[168:171], v[128:131]
	v_mfma_f32_16x16x32_bf16 v[124:127], v[144:147], v[168:171], v[124:127]
	v_mfma_f32_16x16x32_bf16 v[112:115], v[136:139], v[176:179], v[112:115]
	v_mfma_f32_16x16x32_bf16 v[108:111], v[144:147], v[176:179], v[108:111]
	v_mfma_f32_16x16x32_bf16 v[96:99], v[136:139], v[200:203], v[96:99]
	v_mfma_f32_16x16x32_bf16 v[92:95], v[144:147], v[200:203], v[92:95]
	v_mfma_f32_16x16x32_bf16 v[80:83], v[136:139], v[214:217], v[80:83]
	v_mfma_f32_16x16x32_bf16 v[76:79], v[144:147], v[214:217], v[76:79]
	s_setprio 0
	s_setprio 1
	v_mfma_f32_16x16x32_bf16 v[120:123], v[148:151], v[164:167], v[120:123]
	v_mfma_f32_16x16x32_bf16 v[116:119], v[156:159], v[164:167], v[116:119]
	v_mfma_f32_16x16x32_bf16 v[104:107], v[148:151], v[172:175], v[104:107]
	v_mfma_f32_16x16x32_bf16 v[100:103], v[156:159], v[172:175], v[100:103]
	v_mfma_f32_16x16x32_bf16 v[88:91], v[148:151], v[196:199], v[88:91]
	v_mfma_f32_16x16x32_bf16 v[84:87], v[156:159], v[196:199], v[84:87]
	v_mfma_f32_16x16x32_bf16 v[72:75], v[148:151], v[204:207], v[72:75]
	v_mfma_f32_16x16x32_bf16 v[68:71], v[156:159], v[204:207], v[68:71]
	v_mfma_f32_16x16x32_bf16 v[120:123], v[152:155], v[168:171], v[120:123]
	v_mfma_f32_16x16x32_bf16 v[116:119], v[160:163], v[168:171], v[116:119]
	v_mfma_f32_16x16x32_bf16 v[104:107], v[152:155], v[176:179], v[104:107]
	v_mfma_f32_16x16x32_bf16 v[100:103], v[160:163], v[176:179], v[100:103]
	v_mfma_f32_16x16x32_bf16 v[88:91], v[152:155], v[200:203], v[88:91]
	v_mfma_f32_16x16x32_bf16 v[84:87], v[160:163], v[200:203], v[84:87]
	v_mfma_f32_16x16x32_bf16 v[72:75], v[152:155], v[214:217], v[72:75]
	v_mfma_f32_16x16x32_bf16 v[68:71], v[160:163], v[214:217], v[68:71]
	s_setprio 0
	s_barrier
	s_add_i32 s0, s53, s42
	s_mov_b32 m0, s0
	ds_read_b128 v[164:167], v211 offset:16384
	ds_read_b128 v[168:171], v211 offset:17408
	ds_read_b128 v[172:175], v211 offset:18432
	ds_read_b128 v[176:179], v211 offset:19456
	ds_read_b128 v[196:199], v211 offset:20480
	ds_read_b128 v[200:203], v211 offset:21504
	ds_read_b128 v[204:207], v211 offset:22528
	ds_read_b128 v[214:217], v211 offset:23552
	global_load_lds_dwordx4 v182, s[28:29]
	s_add_i32 m0, s0, 0x2000
	s_add_u32 s64, s28, 0x2b0000
	s_addc_u32 s65, s29, 0
	s_add_i32 s0, s54, s42
	global_load_lds_dwordx4 v186, s[28:29]
	s_mov_b32 m0, s0
	s_nop 0
	global_load_lds_dwordx4 v182, s[64:65]
	s_add_i32 m0, s0, 0x2000
	s_nop 0
	global_load_lds_dwordx4 v186, s[64:65]
	s_mov_b32 m0, s43
	s_nop 0
	global_load_lds_dwordx4 v180, s[30:31]
	s_mov_b32 m0, s45
	s_nop 0
	global_load_lds_dwordx4 v184, s[30:31]
	s_waitcnt vmcnt(8)
	s_waitcnt lgkmcnt(0)
	s_barrier
	s_setprio 1
	s_waitcnt lgkmcnt(0)
	v_mfma_f32_16x16x32_bf16 v[64:67], v[132:135], v[164:167], v[64:67]
	v_mfma_f32_16x16x32_bf16 v[60:63], v[140:143], v[164:167], v[60:63]
	v_mfma_f32_16x16x32_bf16 v[48:51], v[132:135], v[172:175], v[48:51]
	v_mfma_f32_16x16x32_bf16 v[44:47], v[140:143], v[172:175], v[44:47]
	v_mfma_f32_16x16x32_bf16 v[32:35], v[132:135], v[196:199], v[32:35]
	v_mfma_f32_16x16x32_bf16 v[28:31], v[140:143], v[196:199], v[28:31]
	v_mfma_f32_16x16x32_bf16 v[16:19], v[132:135], v[204:207], v[16:19]
	v_mfma_f32_16x16x32_bf16 v[12:15], v[140:143], v[204:207], v[12:15]
	v_mfma_f32_16x16x32_bf16 v[64:67], v[136:139], v[168:171], v[64:67]
	v_mfma_f32_16x16x32_bf16 v[60:63], v[144:147], v[168:171], v[60:63]
	v_mfma_f32_16x16x32_bf16 v[48:51], v[136:139], v[176:179], v[48:51]
	v_mfma_f32_16x16x32_bf16 v[44:47], v[144:147], v[176:179], v[44:47]
	v_mfma_f32_16x16x32_bf16 v[32:35], v[136:139], v[200:203], v[32:35]
	v_mfma_f32_16x16x32_bf16 v[28:31], v[144:147], v[200:203], v[28:31]
	v_mfma_f32_16x16x32_bf16 v[16:19], v[136:139], v[214:217], v[16:19]
	v_mfma_f32_16x16x32_bf16 v[12:15], v[144:147], v[214:217], v[12:15]
	s_setprio 0
	s_setprio 1
	v_mfma_f32_16x16x32_bf16 v[56:59], v[148:151], v[164:167], v[56:59]
	v_mfma_f32_16x16x32_bf16 v[52:55], v[156:159], v[164:167], v[52:55]
	v_mfma_f32_16x16x32_bf16 v[40:43], v[148:151], v[172:175], v[40:43]
	v_mfma_f32_16x16x32_bf16 v[36:39], v[156:159], v[172:175], v[36:39]
	v_mfma_f32_16x16x32_bf16 v[24:27], v[148:151], v[196:199], v[24:27]
	v_mfma_f32_16x16x32_bf16 v[20:23], v[156:159], v[196:199], v[20:23]
	v_mfma_f32_16x16x32_bf16 v[8:11], v[148:151], v[204:207], v[8:11]
	v_mfma_f32_16x16x32_bf16 v[4:7], v[156:159], v[204:207], v[4:7]
	v_mfma_f32_16x16x32_bf16 v[56:59], v[152:155], v[168:171], v[56:59]
	v_mfma_f32_16x16x32_bf16 v[52:55], v[160:163], v[168:171], v[52:55]
	v_mfma_f32_16x16x32_bf16 v[40:43], v[152:155], v[176:179], v[40:43]
	v_mfma_f32_16x16x32_bf16 v[36:39], v[160:163], v[176:179], v[36:39]
	v_mfma_f32_16x16x32_bf16 v[24:27], v[152:155], v[200:203], v[24:27]
	v_mfma_f32_16x16x32_bf16 v[20:23], v[160:163], v[200:203], v[20:23]
	v_mfma_f32_16x16x32_bf16 v[8:11], v[152:155], v[214:217], v[8:11]
	v_mfma_f32_16x16x32_bf16 v[4:7], v[160:163], v[214:217], v[4:7]
	s_setprio 0
	s_barrier
	s_add_i32 s0, 0, 0x18000
	s_add_i32 s63, 0, 0x1c000
	v_add_u32_e32 v144, s0, v3
	v_add_u32_e32 v160, s63, v3
	ds_read_b128 v[132:135], v144
	ds_read_b128 v[136:139], v144 offset:1024
	ds_read_b128 v[140:143], v144 offset:2048
	ds_read_b128 v[144:147], v144 offset:3072
	ds_read_b128 v[148:151], v160
	ds_read_b128 v[152:155], v160 offset:1024
	ds_read_b128 v[156:159], v160 offset:2048
	ds_read_b128 v[160:163], v160 offset:3072
	s_add_u32 s98, s30, 0x2b0000
	s_addc_u32 s99, s31, 0
	s_mov_b32 m0, s46
	ds_read_b128 v[164:167], v211 offset:32768
	ds_read_b128 v[168:171], v211 offset:33792
	ds_read_b128 v[172:175], v211 offset:34816
	ds_read_b128 v[176:179], v211 offset:35840
	ds_read_b128 v[196:199], v211 offset:36864
	ds_read_b128 v[200:203], v211 offset:37888
	ds_read_b128 v[204:207], v211 offset:38912
	ds_read_b128 v[214:217], v211 offset:39936
	global_load_lds_dwordx4 v180, s[98:99]
	s_mov_b32 m0, s47
	s_nop 0
	global_load_lds_dwordx4 v184, s[98:99]
	s_waitcnt vmcnt(8)
	s_waitcnt lgkmcnt(0)
	s_barrier
	s_setprio 1
	s_waitcnt lgkmcnt(0)
	v_mfma_f32_16x16x32_bf16 v[128:131], v[132:135], v[164:167], v[128:131]
	v_mfma_f32_16x16x32_bf16 v[124:127], v[140:143], v[164:167], v[124:127]
	v_mfma_f32_16x16x32_bf16 v[112:115], v[132:135], v[172:175], v[112:115]
	v_mfma_f32_16x16x32_bf16 v[108:111], v[140:143], v[172:175], v[108:111]
	v_mfma_f32_16x16x32_bf16 v[96:99], v[132:135], v[196:199], v[96:99]
	v_mfma_f32_16x16x32_bf16 v[92:95], v[140:143], v[196:199], v[92:95]
	v_mfma_f32_16x16x32_bf16 v[80:83], v[132:135], v[204:207], v[80:83]
	v_mfma_f32_16x16x32_bf16 v[76:79], v[140:143], v[204:207], v[76:79]
	v_mfma_f32_16x16x32_bf16 v[128:131], v[136:139], v[168:171], v[128:131]
	v_mfma_f32_16x16x32_bf16 v[124:127], v[144:147], v[168:171], v[124:127]
	v_mfma_f32_16x16x32_bf16 v[112:115], v[136:139], v[176:179], v[112:115]
	v_mfma_f32_16x16x32_bf16 v[108:111], v[144:147], v[176:179], v[108:111]
	v_mfma_f32_16x16x32_bf16 v[96:99], v[136:139], v[200:203], v[96:99]
	v_mfma_f32_16x16x32_bf16 v[92:95], v[144:147], v[200:203], v[92:95]
	v_mfma_f32_16x16x32_bf16 v[80:83], v[136:139], v[214:217], v[80:83]
	v_mfma_f32_16x16x32_bf16 v[76:79], v[144:147], v[214:217], v[76:79]
	s_setprio 0
	s_setprio 1
	v_mfma_f32_16x16x32_bf16 v[120:123], v[148:151], v[164:167], v[120:123]
	v_mfma_f32_16x16x32_bf16 v[116:119], v[156:159], v[164:167], v[116:119]
	v_mfma_f32_16x16x32_bf16 v[104:107], v[148:151], v[172:175], v[104:107]
	v_mfma_f32_16x16x32_bf16 v[100:103], v[156:159], v[172:175], v[100:103]
	v_mfma_f32_16x16x32_bf16 v[88:91], v[148:151], v[196:199], v[88:91]
	v_mfma_f32_16x16x32_bf16 v[84:87], v[156:159], v[196:199], v[84:87]
	v_mfma_f32_16x16x32_bf16 v[72:75], v[148:151], v[204:207], v[72:75]
	v_mfma_f32_16x16x32_bf16 v[68:71], v[156:159], v[204:207], v[68:71]
	v_mfma_f32_16x16x32_bf16 v[120:123], v[152:155], v[168:171], v[120:123]
	v_mfma_f32_16x16x32_bf16 v[116:119], v[160:163], v[168:171], v[116:119]
	v_mfma_f32_16x16x32_bf16 v[104:107], v[152:155], v[176:179], v[104:107]
	v_mfma_f32_16x16x32_bf16 v[100:103], v[160:163], v[176:179], v[100:103]
	v_mfma_f32_16x16x32_bf16 v[88:91], v[152:155], v[200:203], v[88:91]
	v_mfma_f32_16x16x32_bf16 v[84:87], v[160:163], v[200:203], v[84:87]
	v_mfma_f32_16x16x32_bf16 v[72:75], v[152:155], v[214:217], v[72:75]
	v_mfma_f32_16x16x32_bf16 v[68:71], v[160:163], v[214:217], v[68:71]
	s_setprio 0
	s_barrier
	s_add_i32 s0, s0, s42
	s_add_i32 m0, s0, 0xffffff80
	ds_read_b128 v[164:167], v211 offset:49152
	ds_read_b128 v[168:171], v211 offset:50176
	ds_read_b128 v[172:175], v211 offset:51200
	ds_read_b128 v[176:179], v211 offset:52224
	ds_read_b128 v[196:199], v211 offset:53248
	ds_read_b128 v[200:203], v211 offset:54272
	ds_read_b128 v[204:207], v211 offset:55296
	ds_read_b128 v[214:217], v211 offset:56320
	global_load_lds_dwordx4 v182, s[28:29] offset:128
	s_add_i32 m0, s0, 0x1f80
	s_add_i32 s0, s63, s42
	global_load_lds_dwordx4 v186, s[28:29] offset:128
	s_add_u32 s28, s28, 0x2b0080
	s_addc_u32 s29, s29, 0
	s_mov_b32 m0, s0
	s_nop 0
	global_load_lds_dwordx4 v182, s[28:29]
	s_add_i32 m0, s0, 0x2000
	s_nop 0
	global_load_lds_dwordx4 v186, s[28:29]
	s_add_i32 m0, s51, 0xffffff80
	s_nop 0
	global_load_lds_dwordx4 v180, s[30:31] offset:128
	s_add_i32 m0, s52, 0xffffff80
	s_nop 0
	global_load_lds_dwordx4 v184, s[30:31] offset:128
	s_waitcnt vmcnt(8)
	s_waitcnt lgkmcnt(0)
	s_barrier
	s_setprio 1
	s_waitcnt lgkmcnt(0)
	v_mfma_f32_16x16x32_bf16 v[64:67], v[132:135], v[164:167], v[64:67]
	v_mfma_f32_16x16x32_bf16 v[60:63], v[140:143], v[164:167], v[60:63]
	v_mfma_f32_16x16x32_bf16 v[48:51], v[132:135], v[172:175], v[48:51]
	v_mfma_f32_16x16x32_bf16 v[44:47], v[140:143], v[172:175], v[44:47]
	v_mfma_f32_16x16x32_bf16 v[32:35], v[132:135], v[196:199], v[32:35]
	v_mfma_f32_16x16x32_bf16 v[28:31], v[140:143], v[196:199], v[28:31]
	v_mfma_f32_16x16x32_bf16 v[16:19], v[132:135], v[204:207], v[16:19]
	v_mfma_f32_16x16x32_bf16 v[12:15], v[140:143], v[204:207], v[12:15]
	v_mfma_f32_16x16x32_bf16 v[64:67], v[136:139], v[168:171], v[64:67]
	v_mfma_f32_16x16x32_bf16 v[60:63], v[144:147], v[168:171], v[60:63]
	v_mfma_f32_16x16x32_bf16 v[48:51], v[136:139], v[176:179], v[48:51]
	v_mfma_f32_16x16x32_bf16 v[44:47], v[144:147], v[176:179], v[44:47]
	v_mfma_f32_16x16x32_bf16 v[32:35], v[136:139], v[200:203], v[32:35]
	v_mfma_f32_16x16x32_bf16 v[28:31], v[144:147], v[200:203], v[28:31]
	v_mfma_f32_16x16x32_bf16 v[16:19], v[136:139], v[214:217], v[16:19]
	v_mfma_f32_16x16x32_bf16 v[12:15], v[144:147], v[214:217], v[12:15]
	s_setprio 0
	s_setprio 1
	v_mfma_f32_16x16x32_bf16 v[56:59], v[148:151], v[164:167], v[56:59]
	v_mfma_f32_16x16x32_bf16 v[52:55], v[156:159], v[164:167], v[52:55]
	v_mfma_f32_16x16x32_bf16 v[40:43], v[148:151], v[172:175], v[40:43]
	v_mfma_f32_16x16x32_bf16 v[36:39], v[156:159], v[172:175], v[36:39]
	v_mfma_f32_16x16x32_bf16 v[24:27], v[148:151], v[196:199], v[24:27]
	v_mfma_f32_16x16x32_bf16 v[20:23], v[156:159], v[196:199], v[20:23]
	v_mfma_f32_16x16x32_bf16 v[8:11], v[148:151], v[204:207], v[8:11]
	v_mfma_f32_16x16x32_bf16 v[4:7], v[156:159], v[204:207], v[4:7]
	v_mfma_f32_16x16x32_bf16 v[56:59], v[152:155], v[168:171], v[56:59]
	v_mfma_f32_16x16x32_bf16 v[52:55], v[160:163], v[168:171], v[52:55]
	v_mfma_f32_16x16x32_bf16 v[40:43], v[152:155], v[176:179], v[40:43]
	v_mfma_f32_16x16x32_bf16 v[36:39], v[160:163], v[176:179], v[36:39]
	v_mfma_f32_16x16x32_bf16 v[24:27], v[152:155], v[200:203], v[24:27]
	v_mfma_f32_16x16x32_bf16 v[20:23], v[160:163], v[200:203], v[20:23]
	v_mfma_f32_16x16x32_bf16 v[8:11], v[152:155], v[214:217], v[8:11]
	v_mfma_f32_16x16x32_bf16 v[4:7], v[160:163], v[214:217], v[4:7]
	s_setprio 0
	s_barrier
	s_add_i32 s62, s62, 2
	s_add_u32 s26, s26, 0x100
	s_addc_u32 s27, s27, 0
	s_add_u32 s60, s60, 0x100
	s_addc_u32 s61, s61, 0
	s_cmpk_gt_u32 s62, 0xa9
	s_cbranch_scc0 .LBB0_342
	s_and_b64 vcc, exec, s[22:23]
	s_cbranch_vccz .LBB0_345
	s_barrier

.LBB0_429:
	ds_read_b128 v[150:153], v156
	ds_read_b128 v[162:165], v156 offset:1024
	ds_read_b128 v[166:169], v156 offset:2048
	ds_read_b128 v[170:173], v156 offset:3072
	ds_read_b128 v[174:177], v157
	ds_read_b128 v[178:181], v157 offset:1024
	ds_read_b128 v[182:185], v157 offset:2048
	ds_read_b128 v[186:189], v157 offset:3072
	s_add_u32 s0, s50, 0xfff00080
	s_addc_u32 s52, s51, -1
	s_cmp_eq_u32 s72, 60
	s_cselect_b32 s55, s27, s52
	s_cselect_b32 s54, s67, s0
	s_cselect_b32 s53, s25, s71
	s_cselect_b32 s52, s68, s70
	s_add_i32 m0, s43, 0xc000
	ds_read_b128 v[190:193], v158
	ds_read_b128 v[194:197], v158 offset:1024
	ds_read_b128 v[198:201], v158 offset:2048
	ds_read_b128 v[202:205], v158 offset:3072
	ds_read_b128 v[206:209], v158 offset:4096
	ds_read_b128 v[210:213], v158 offset:5120
	ds_read_b128 v[214:217], v158 offset:6144
	ds_read_b128 v[218:221], v158 offset:7168
	global_load_lds_dwordx4 v142, s[50:51]
	s_add_i32 m0, s43, 0xe000
	s_nop 0
	global_load_lds_dwordx4 v144, s[50:51]
	s_waitcnt vmcnt(8)
	s_waitcnt lgkmcnt(0)
	s_barrier
	s_setprio 1
	s_waitcnt lgkmcnt(0)
	v_mfma_f32_16x16x32_bf16 v[128:131], v[150:153], v[190:193], v[128:131]
	v_mfma_f32_16x16x32_bf16 v[124:127], v[166:169], v[190:193], v[124:127]
	v_mfma_f32_16x16x32_bf16 v[112:115], v[150:153], v[198:201], v[112:115]
	v_mfma_f32_16x16x32_bf16 v[108:111], v[166:169], v[198:201], v[108:111]
	v_mfma_f32_16x16x32_bf16 v[96:99], v[150:153], v[206:209], v[96:99]
	v_mfma_f32_16x16x32_bf16 v[92:95], v[166:169], v[206:209], v[92:95]
	v_mfma_f32_16x16x32_bf16 v[80:83], v[150:153], v[214:217], v[80:83]
	v_mfma_f32_16x16x32_bf16 v[76:79], v[166:169], v[214:217], v[76:79]
	v_mfma_f32_16x16x32_bf16 v[128:131], v[162:165], v[194:197], v[128:131]
	v_mfma_f32_16x16x32_bf16 v[124:127], v[170:173], v[194:197], v[124:127]
	v_mfma_f32_16x16x32_bf16 v[112:115], v[162:165], v[202:205], v[112:115]
	v_mfma_f32_16x16x32_bf16 v[108:111], v[170:173], v[202:205], v[108:111]
	v_mfma_f32_16x16x32_bf16 v[96:99], v[162:165], v[210:213], v[96:99]
	v_mfma_f32_16x16x32_bf16 v[92:95], v[170:173], v[210:213], v[92:95]
	v_mfma_f32_16x16x32_bf16 v[80:83], v[162:165], v[218:221], v[80:83]
	v_mfma_f32_16x16x32_bf16 v[76:79], v[170:173], v[218:221], v[76:79]
	s_setprio 0
	s_setprio 1
	v_mfma_f32_16x16x32_bf16 v[120:123], v[174:177], v[190:193], v[120:123]
	v_mfma_f32_16x16x32_bf16 v[116:119], v[182:185], v[190:193], v[116:119]
	v_mfma_f32_16x16x32_bf16 v[104:107], v[174:177], v[198:201], v[104:107]
	v_mfma_f32_16x16x32_bf16 v[100:103], v[182:185], v[198:201], v[100:103]
	v_mfma_f32_16x16x32_bf16 v[88:91], v[174:177], v[206:209], v[88:91]
	v_mfma_f32_16x16x32_bf16 v[84:87], v[182:185], v[206:209], v[84:87]
	v_mfma_f32_16x16x32_bf16 v[72:75], v[174:177], v[214:217], v[72:75]
	v_mfma_f32_16x16x32_bf16 v[68:71], v[182:185], v[214:217], v[68:71]
	v_mfma_f32_16x16x32_bf16 v[120:123], v[178:181], v[194:197], v[120:123]
	v_mfma_f32_16x16x32_bf16 v[116:119], v[186:189], v[194:197], v[116:119]
	v_mfma_f32_16x16x32_bf16 v[104:107], v[178:181], v[202:205], v[104:107]
	v_mfma_f32_16x16x32_bf16 v[100:103], v[186:189], v[202:205], v[100:103]
	v_mfma_f32_16x16x32_bf16 v[88:91], v[178:181], v[210:213], v[88:91]
	v_mfma_f32_16x16x32_bf16 v[84:87], v[186:189], v[210:213], v[84:87]
	v_mfma_f32_16x16x32_bf16 v[72:75], v[178:181], v[218:221], v[72:75]
	v_mfma_f32_16x16x32_bf16 v[68:71], v[186:189], v[218:221], v[68:71]
	s_setprio 0
	s_barrier
	s_add_i32 s0, s62, s41
	s_mov_b32 m0, s0
	ds_read_b128 v[190:193], v158 offset:16384
	ds_read_b128 v[194:197], v158 offset:17408
	ds_read_b128 v[198:201], v158 offset:18432
	ds_read_b128 v[202:205], v158 offset:19456
	ds_read_b128 v[206:209], v158 offset:20480
	ds_read_b128 v[210:213], v158 offset:21504
	ds_read_b128 v[214:217], v158 offset:22528
	ds_read_b128 v[218:221], v158 offset:23552
	global_load_lds_dwordx4 v136, s[52:53]
	s_add_i32 m0, s0, 0x2000
	s_add_u32 s74, s52, 0x100000
	s_addc_u32 s75, s53, 0
	s_add_i32 s0, s63, s41
	global_load_lds_dwordx4 v140, s[52:53]
	s_mov_b32 m0, s0
	s_nop 0
	global_load_lds_dwordx4 v136, s[74:75]
	s_add_i32 m0, s0, 0x2000
	s_nop 0
	global_load_lds_dwordx4 v140, s[74:75]
	s_mov_b32 m0, s43
	s_nop 0
	global_load_lds_dwordx4 v134, s[54:55]
	s_mov_b32 m0, s48
	s_nop 0
	global_load_lds_dwordx4 v138, s[54:55]
	s_waitcnt vmcnt(8)
	s_waitcnt lgkmcnt(0)
	s_barrier
	s_setprio 1
	s_waitcnt lgkmcnt(0)
	v_mfma_f32_16x16x32_bf16 v[64:67], v[150:153], v[190:193], v[64:67]
	v_mfma_f32_16x16x32_bf16 v[60:63], v[166:169], v[190:193], v[60:63]
	v_mfma_f32_16x16x32_bf16 v[48:51], v[150:153], v[198:201], v[48:51]
	v_mfma_f32_16x16x32_bf16 v[44:47], v[166:169], v[198:201], v[44:47]
	v_mfma_f32_16x16x32_bf16 v[32:35], v[150:153], v[206:209], v[32:35]
	v_mfma_f32_16x16x32_bf16 v[28:31], v[166:169], v[206:209], v[28:31]
	v_mfma_f32_16x16x32_bf16 v[16:19], v[150:153], v[214:217], v[16:19]
	v_mfma_f32_16x16x32_bf16 v[12:15], v[166:169], v[214:217], v[12:15]
	v_mfma_f32_16x16x32_bf16 v[64:67], v[162:165], v[194:197], v[64:67]
	v_mfma_f32_16x16x32_bf16 v[60:63], v[170:173], v[194:197], v[60:63]
	v_mfma_f32_16x16x32_bf16 v[48:51], v[162:165], v[202:205], v[48:51]
	v_mfma_f32_16x16x32_bf16 v[44:47], v[170:173], v[202:205], v[44:47]
	v_mfma_f32_16x16x32_bf16 v[32:35], v[162:165], v[210:213], v[32:35]
	v_mfma_f32_16x16x32_bf16 v[28:31], v[170:173], v[210:213], v[28:31]
	v_mfma_f32_16x16x32_bf16 v[16:19], v[162:165], v[218:221], v[16:19]
	v_mfma_f32_16x16x32_bf16 v[12:15], v[170:173], v[218:221], v[12:15]
	s_setprio 0
	s_setprio 1
	v_mfma_f32_16x16x32_bf16 v[56:59], v[174:177], v[190:193], v[56:59]
	v_mfma_f32_16x16x32_bf16 v[52:55], v[182:185], v[190:193], v[52:55]
	v_mfma_f32_16x16x32_bf16 v[40:43], v[174:177], v[198:201], v[40:43]
	v_mfma_f32_16x16x32_bf16 v[36:39], v[182:185], v[198:201], v[36:39]
	v_mfma_f32_16x16x32_bf16 v[24:27], v[174:177], v[206:209], v[24:27]
	v_mfma_f32_16x16x32_bf16 v[20:23], v[182:185], v[206:209], v[20:23]
	v_mfma_f32_16x16x32_bf16 v[8:11], v[174:177], v[214:217], v[8:11]
	v_mfma_f32_16x16x32_bf16 v[4:7], v[182:185], v[214:217], v[4:7]
	v_mfma_f32_16x16x32_bf16 v[56:59], v[178:181], v[194:197], v[56:59]
	v_mfma_f32_16x16x32_bf16 v[52:55], v[186:189], v[194:197], v[52:55]
	v_mfma_f32_16x16x32_bf16 v[40:43], v[178:181], v[202:205], v[40:43]
	v_mfma_f32_16x16x32_bf16 v[36:39], v[186:189], v[202:205], v[36:39]
	v_mfma_f32_16x16x32_bf16 v[24:27], v[178:181], v[210:213], v[24:27]
	v_mfma_f32_16x16x32_bf16 v[20:23], v[186:189], v[210:213], v[20:23]
	v_mfma_f32_16x16x32_bf16 v[8:11], v[178:181], v[218:221], v[8:11]
	v_mfma_f32_16x16x32_bf16 v[4:7], v[186:189], v[218:221], v[4:7]
	s_setprio 0
	s_barrier
	s_add_i32 s0, 0, 0x18000
	v_add_u32_e32 v161, s0, v133
	s_add_i32 s73, 0, 0x1c000
	ds_read_b128 v[150:153], v161
	ds_read_b128 v[162:165], v161 offset:1024
	ds_read_b128 v[166:169], v161 offset:2048
	ds_read_b128 v[170:173], v161 offset:3072
	v_add_u32_e32 v161, s73, v133
	ds_read_b128 v[174:177], v161
	ds_read_b128 v[178:181], v161 offset:1024
	ds_read_b128 v[182:185], v161 offset:2048
	ds_read_b128 v[186:189], v161 offset:3072
	s_add_u32 s98, s54, 0x100000
	s_addc_u32 s99, s55, 0
	s_mov_b32 m0, s49
	ds_read_b128 v[190:193], v158 offset:32768
	ds_read_b128 v[194:197], v158 offset:33792
	ds_read_b128 v[198:201], v158 offset:34816
	ds_read_b128 v[202:205], v158 offset:35840
	ds_read_b128 v[206:209], v158 offset:36864
	ds_read_b128 v[210:213], v158 offset:37888
	ds_read_b128 v[214:217], v158 offset:38912
	ds_read_b128 v[218:221], v158 offset:39936
	global_load_lds_dwordx4 v134, s[98:99]
	s_mov_b32 m0, s56
	s_nop 0
	global_load_lds_dwordx4 v138, s[98:99]
	s_waitcnt vmcnt(8)
	s_waitcnt lgkmcnt(0)
	s_barrier
	s_setprio 1
	s_waitcnt lgkmcnt(0)
	v_mfma_f32_16x16x32_bf16 v[128:131], v[150:153], v[190:193], v[128:131]
	v_mfma_f32_16x16x32_bf16 v[124:127], v[166:169], v[190:193], v[124:127]
	v_mfma_f32_16x16x32_bf16 v[112:115], v[150:153], v[198:201], v[112:115]
	v_mfma_f32_16x16x32_bf16 v[108:111], v[166:169], v[198:201], v[108:111]
	v_mfma_f32_16x16x32_bf16 v[96:99], v[150:153], v[206:209], v[96:99]
	v_mfma_f32_16x16x32_bf16 v[92:95], v[166:169], v[206:209], v[92:95]
	v_mfma_f32_16x16x32_bf16 v[80:83], v[150:153], v[214:217], v[80:83]
	v_mfma_f32_16x16x32_bf16 v[76:79], v[166:169], v[214:217], v[76:79]
	v_mfma_f32_16x16x32_bf16 v[128:131], v[162:165], v[194:197], v[128:131]
	v_mfma_f32_16x16x32_bf16 v[124:127], v[170:173], v[194:197], v[124:127]
	v_mfma_f32_16x16x32_bf16 v[112:115], v[162:165], v[202:205], v[112:115]
	v_mfma_f32_16x16x32_bf16 v[108:111], v[170:173], v[202:205], v[108:111]
	v_mfma_f32_16x16x32_bf16 v[96:99], v[162:165], v[210:213], v[96:99]
	v_mfma_f32_16x16x32_bf16 v[92:95], v[170:173], v[210:213], v[92:95]
	v_mfma_f32_16x16x32_bf16 v[80:83], v[162:165], v[218:221], v[80:83]
	v_mfma_f32_16x16x32_bf16 v[76:79], v[170:173], v[218:221], v[76:79]
	s_setprio 0
	s_setprio 1
	v_mfma_f32_16x16x32_bf16 v[120:123], v[174:177], v[190:193], v[120:123]
	v_mfma_f32_16x16x32_bf16 v[116:119], v[182:185], v[190:193], v[116:119]
	v_mfma_f32_16x16x32_bf16 v[104:107], v[174:177], v[198:201], v[104:107]
	v_mfma_f32_16x16x32_bf16 v[100:103], v[182:185], v[198:201], v[100:103]
	v_mfma_f32_16x16x32_bf16 v[88:91], v[174:177], v[206:209], v[88:91]
	v_mfma_f32_16x16x32_bf16 v[84:87], v[182:185], v[206:209], v[84:87]
	v_mfma_f32_16x16x32_bf16 v[72:75], v[174:177], v[214:217], v[72:75]
	v_mfma_f32_16x16x32_bf16 v[68:71], v[182:185], v[214:217], v[68:71]
	v_mfma_f32_16x16x32_bf16 v[120:123], v[178:181], v[194:197], v[120:123]
	v_mfma_f32_16x16x32_bf16 v[116:119], v[186:189], v[194:197], v[116:119]
	v_mfma_f32_16x16x32_bf16 v[104:107], v[178:181], v[202:205], v[104:107]
	v_mfma_f32_16x16x32_bf16 v[100:103], v[186:189], v[202:205], v[100:103]
	v_mfma_f32_16x16x32_bf16 v[88:91], v[178:181], v[210:213], v[88:91]
	v_mfma_f32_16x16x32_bf16 v[84:87], v[186:189], v[210:213], v[84:87]
	v_mfma_f32_16x16x32_bf16 v[72:75], v[178:181], v[218:221], v[72:75]
	v_mfma_f32_16x16x32_bf16 v[68:71], v[186:189], v[218:221], v[68:71]
	s_setprio 0
	s_barrier
	s_add_i32 s0, s0, s41
	s_add_i32 m0, s0, 0xffffff80
	ds_read_b128 v[190:193], v158 offset:49152
	ds_read_b128 v[194:197], v158 offset:50176
	ds_read_b128 v[198:201], v158 offset:51200
	ds_read_b128 v[202:205], v158 offset:52224
	ds_read_b128 v[206:209], v158 offset:53248
	ds_read_b128 v[210:213], v158 offset:54272
	ds_read_b128 v[214:217], v158 offset:55296
	ds_read_b128 v[218:221], v158 offset:56320
	global_load_lds_dwordx4 v136, s[52:53] offset:128
	s_add_i32 m0, s0, 0x1f80
	s_add_i32 s0, s73, s41
	global_load_lds_dwordx4 v140, s[52:53] offset:128
	s_add_u32 s52, s52, 0x100080
	s_addc_u32 s53, s53, 0
	s_mov_b32 m0, s0
	s_nop 0
	global_load_lds_dwordx4 v136, s[52:53]
	s_add_i32 m0, s0, 0x2000
	s_nop 0
	global_load_lds_dwordx4 v140, s[52:53]
	s_add_i32 m0, s59, 0xffffff80
	s_nop 0
	global_load_lds_dwordx4 v134, s[54:55] offset:128
	s_add_i32 m0, s60, 0xffffff80
	s_nop 0
	global_load_lds_dwordx4 v138, s[54:55] offset:128
	s_waitcnt vmcnt(8)
	s_waitcnt lgkmcnt(0)
	s_barrier
	s_setprio 1
	s_waitcnt lgkmcnt(0)
	v_mfma_f32_16x16x32_bf16 v[64:67], v[150:153], v[190:193], v[64:67]
	v_mfma_f32_16x16x32_bf16 v[60:63], v[166:169], v[190:193], v[60:63]
	v_mfma_f32_16x16x32_bf16 v[48:51], v[150:153], v[198:201], v[48:51]
	v_mfma_f32_16x16x32_bf16 v[44:47], v[166:169], v[198:201], v[44:47]
	v_mfma_f32_16x16x32_bf16 v[32:35], v[150:153], v[206:209], v[32:35]
	v_mfma_f32_16x16x32_bf16 v[28:31], v[166:169], v[206:209], v[28:31]
	v_mfma_f32_16x16x32_bf16 v[16:19], v[150:153], v[214:217], v[16:19]
	v_mfma_f32_16x16x32_bf16 v[12:15], v[166:169], v[214:217], v[12:15]
	v_mfma_f32_16x16x32_bf16 v[64:67], v[162:165], v[194:197], v[64:67]
	v_mfma_f32_16x16x32_bf16 v[60:63], v[170:173], v[194:197], v[60:63]
	v_mfma_f32_16x16x32_bf16 v[48:51], v[162:165], v[202:205], v[48:51]
	v_mfma_f32_16x16x32_bf16 v[44:47], v[170:173], v[202:205], v[44:47]
	v_mfma_f32_16x16x32_bf16 v[32:35], v[162:165], v[210:213], v[32:35]
	v_mfma_f32_16x16x32_bf16 v[28:31], v[170:173], v[210:213], v[28:31]
	v_mfma_f32_16x16x32_bf16 v[16:19], v[162:165], v[218:221], v[16:19]
	v_mfma_f32_16x16x32_bf16 v[12:15], v[170:173], v[218:221], v[12:15]
	s_setprio 0
	s_setprio 1
	v_mfma_f32_16x16x32_bf16 v[56:59], v[174:177], v[190:193], v[56:59]
	v_mfma_f32_16x16x32_bf16 v[52:55], v[182:185], v[190:193], v[52:55]
	v_mfma_f32_16x16x32_bf16 v[40:43], v[174:177], v[198:201], v[40:43]
	v_mfma_f32_16x16x32_bf16 v[36:39], v[182:185], v[198:201], v[36:39]
	v_mfma_f32_16x16x32_bf16 v[24:27], v[174:177], v[206:209], v[24:27]
	v_mfma_f32_16x16x32_bf16 v[20:23], v[182:185], v[206:209], v[20:23]
	v_mfma_f32_16x16x32_bf16 v[8:11], v[174:177], v[214:217], v[8:11]
	v_mfma_f32_16x16x32_bf16 v[4:7], v[182:185], v[214:217], v[4:7]
	v_mfma_f32_16x16x32_bf16 v[56:59], v[178:181], v[194:197], v[56:59]
	v_mfma_f32_16x16x32_bf16 v[52:55], v[186:189], v[194:197], v[52:55]
	v_mfma_f32_16x16x32_bf16 v[40:43], v[178:181], v[202:205], v[40:43]
	v_mfma_f32_16x16x32_bf16 v[36:39], v[186:189], v[202:205], v[36:39]
	v_mfma_f32_16x16x32_bf16 v[24:27], v[178:181], v[210:213], v[24:27]
	v_mfma_f32_16x16x32_bf16 v[20:23], v[186:189], v[210:213], v[20:23]
	v_mfma_f32_16x16x32_bf16 v[8:11], v[178:181], v[218:221], v[8:11]
	v_mfma_f32_16x16x32_bf16 v[4:7], v[186:189], v[218:221], v[4:7]
	s_setprio 0
	s_barrier
	s_add_i32 s72, s72, 2
	s_add_u32 s50, s50, 0x100
	s_addc_u32 s51, s51, 0
	s_add_u32 s70, s70, 0x100
	s_addc_u32 s71, s71, 0
	s_cmp_gt_u32 s72, 61
	s_cbranch_scc0 .LBB0_429
	s_and_b64 vcc, exec, s[22:23]
	s_cbranch_vccz .LBB0_432
	s_barrier

.LBB0_1032:
	v_add_u32_e32 v5, s60, v3
	ds_read_b128 v[140:143], v5
	ds_read_b128 v[144:147], v5 offset:1024
	ds_read_b128 v[148:151], v5 offset:2048
	ds_read_b128 v[152:155], v5 offset:3072
	v_add_u32_e32 v5, s61, v3
	ds_read_b128 v[156:159], v5
	ds_read_b128 v[160:163], v5 offset:1024
	ds_read_b128 v[164:167], v5 offset:2048
	ds_read_b128 v[168:171], v5 offset:3072
	s_add_u32 s42, s40, 0xfff80080
	s_addc_u32 s43, s41, -1
	s_cmp_eq_u32 s67, 28
	s_cselect_b32 s51, s5, s43
	s_cselect_b32 s50, s7, s42
	s_cselect_b32 s43, s25, s66
	s_cselect_b32 s42, s27, s65
	s_add_i32 m0, s47, 0xc000
	ds_read_b128 v[172:175], v246
	ds_read_b128 v[176:179], v246 offset:1024
	ds_read_b128 v[180:183], v246 offset:2048
	ds_read_b128 v[184:187], v246 offset:3072
	ds_read_b128 v[188:191], v246 offset:4096
	ds_read_b128 v[192:195], v246 offset:5120
	ds_read_b128 v[196:199], v246 offset:6144
	ds_read_b128 v[200:203], v246 offset:7168
	global_load_lds_dwordx4 v216, s[40:41]
	s_add_i32 m0, s47, 0xe000
	s_nop 0
	global_load_lds_dwordx4 v218, s[40:41]
	s_waitcnt vmcnt(8)
	s_waitcnt lgkmcnt(0)
	s_barrier
	s_setprio 1
	s_waitcnt lgkmcnt(0)
	v_mfma_f32_16x16x32_bf16 v[136:139], v[140:143], v[172:175], v[136:139]
	v_mfma_f32_16x16x32_bf16 v[132:135], v[148:151], v[172:175], v[132:135]
	v_mfma_f32_16x16x32_bf16 v[128:131], v[140:143], v[180:183], v[128:131]
	v_mfma_f32_16x16x32_bf16 v[124:127], v[148:151], v[180:183], v[124:127]
	v_mfma_f32_16x16x32_bf16 v[120:123], v[140:143], v[188:191], v[120:123]
	v_mfma_f32_16x16x32_bf16 v[116:119], v[148:151], v[188:191], v[116:119]
	v_mfma_f32_16x16x32_bf16 v[112:115], v[140:143], v[196:199], v[112:115]
	v_mfma_f32_16x16x32_bf16 v[108:111], v[148:151], v[196:199], v[108:111]
	v_mfma_f32_16x16x32_bf16 v[136:139], v[144:147], v[176:179], v[136:139]
	v_mfma_f32_16x16x32_bf16 v[132:135], v[152:155], v[176:179], v[132:135]
	v_mfma_f32_16x16x32_bf16 v[128:131], v[144:147], v[184:187], v[128:131]
	v_mfma_f32_16x16x32_bf16 v[124:127], v[152:155], v[184:187], v[124:127]
	v_mfma_f32_16x16x32_bf16 v[120:123], v[144:147], v[192:195], v[120:123]
	v_mfma_f32_16x16x32_bf16 v[116:119], v[152:155], v[192:195], v[116:119]
	v_mfma_f32_16x16x32_bf16 v[112:115], v[144:147], v[200:203], v[112:115]
	v_mfma_f32_16x16x32_bf16 v[108:111], v[152:155], v[200:203], v[108:111]
	s_setprio 0
	s_setprio 1
	v_mfma_f32_16x16x32_bf16 v[104:107], v[156:159], v[172:175], v[104:107]
	v_mfma_f32_16x16x32_bf16 v[100:103], v[164:167], v[172:175], v[100:103]
	v_mfma_f32_16x16x32_bf16 v[96:99], v[156:159], v[180:183], v[96:99]
	v_mfma_f32_16x16x32_bf16 v[92:95], v[164:167], v[180:183], v[92:95]
	v_mfma_f32_16x16x32_bf16 v[88:91], v[156:159], v[188:191], v[88:91]
	v_mfma_f32_16x16x32_bf16 v[84:87], v[164:167], v[188:191], v[84:87]
	v_mfma_f32_16x16x32_bf16 v[80:83], v[156:159], v[196:199], v[80:83]
	v_mfma_f32_16x16x32_bf16 v[76:79], v[164:167], v[196:199], v[76:79]
	v_mfma_f32_16x16x32_bf16 v[104:107], v[160:163], v[176:179], v[104:107]
	v_mfma_f32_16x16x32_bf16 v[100:103], v[168:171], v[176:179], v[100:103]
	v_mfma_f32_16x16x32_bf16 v[96:99], v[160:163], v[184:187], v[96:99]
	v_mfma_f32_16x16x32_bf16 v[92:95], v[168:171], v[184:187], v[92:95]
	v_mfma_f32_16x16x32_bf16 v[88:91], v[160:163], v[192:195], v[88:91]
	v_mfma_f32_16x16x32_bf16 v[84:87], v[168:171], v[192:195], v[84:87]
	v_mfma_f32_16x16x32_bf16 v[80:83], v[160:163], v[200:203], v[80:83]
	v_mfma_f32_16x16x32_bf16 v[76:79], v[168:171], v[200:203], v[76:79]
	s_setprio 0
	s_barrier
	s_add_i32 s68, s60, s46
	s_mov_b32 m0, s68
	ds_read_b128 v[172:175], v246 offset:16384
	ds_read_b128 v[176:179], v246 offset:17408
	ds_read_b128 v[180:183], v246 offset:18432
	ds_read_b128 v[184:187], v246 offset:19456
	ds_read_b128 v[188:191], v246 offset:20480
	ds_read_b128 v[192:195], v246 offset:21504
	ds_read_b128 v[196:199], v246 offset:22528
	ds_read_b128 v[200:203], v246 offset:23552
	global_load_lds_dwordx4 v210, s[42:43]
	s_add_i32 m0, s68, 0x2000
	s_add_u32 s70, s42, 0x80000
	s_addc_u32 s71, s43, 0
	s_add_i32 s68, s61, s46
	global_load_lds_dwordx4 v214, s[42:43]
	s_mov_b32 m0, s68
	s_nop 0
	global_load_lds_dwordx4 v210, s[70:71]
	s_add_i32 m0, s68, 0x2000
	s_nop 0
	global_load_lds_dwordx4 v214, s[70:71]
	s_mov_b32 m0, s47
	s_nop 0
	global_load_lds_dwordx4 v208, s[50:51]
	s_mov_b32 m0, s48
	s_nop 0
	global_load_lds_dwordx4 v212, s[50:51]
	s_waitcnt vmcnt(8)
	s_waitcnt lgkmcnt(0)
	s_barrier
	s_setprio 1
	s_waitcnt lgkmcnt(0)
	v_mfma_f32_16x16x32_bf16 v[72:75], v[140:143], v[172:175], v[72:75]
	v_mfma_f32_16x16x32_bf16 v[68:71], v[148:151], v[172:175], v[68:71]
	v_mfma_f32_16x16x32_bf16 v[64:67], v[140:143], v[180:183], v[64:67]
	v_mfma_f32_16x16x32_bf16 v[60:63], v[148:151], v[180:183], v[60:63]
	v_mfma_f32_16x16x32_bf16 v[56:59], v[140:143], v[188:191], v[56:59]
	v_mfma_f32_16x16x32_bf16 v[52:55], v[148:151], v[188:191], v[52:55]
	v_mfma_f32_16x16x32_bf16 v[48:51], v[140:143], v[196:199], v[48:51]
	v_mfma_f32_16x16x32_bf16 v[44:47], v[148:151], v[196:199], v[44:47]
	v_mfma_f32_16x16x32_bf16 v[72:75], v[144:147], v[176:179], v[72:75]
	v_mfma_f32_16x16x32_bf16 v[68:71], v[152:155], v[176:179], v[68:71]
	v_mfma_f32_16x16x32_bf16 v[64:67], v[144:147], v[184:187], v[64:67]
	v_mfma_f32_16x16x32_bf16 v[60:63], v[152:155], v[184:187], v[60:63]
	v_mfma_f32_16x16x32_bf16 v[56:59], v[144:147], v[192:195], v[56:59]
	v_mfma_f32_16x16x32_bf16 v[52:55], v[152:155], v[192:195], v[52:55]
	v_mfma_f32_16x16x32_bf16 v[48:51], v[144:147], v[200:203], v[48:51]
	v_mfma_f32_16x16x32_bf16 v[44:47], v[152:155], v[200:203], v[44:47]
	s_setprio 0
	s_setprio 1
	v_mfma_f32_16x16x32_bf16 v[40:43], v[156:159], v[172:175], v[40:43]
	v_mfma_f32_16x16x32_bf16 v[36:39], v[164:167], v[172:175], v[36:39]
	v_mfma_f32_16x16x32_bf16 v[32:35], v[156:159], v[180:183], v[32:35]
	v_mfma_f32_16x16x32_bf16 v[28:31], v[164:167], v[180:183], v[28:31]
	v_mfma_f32_16x16x32_bf16 v[24:27], v[156:159], v[188:191], v[24:27]
	v_mfma_f32_16x16x32_bf16 v[20:23], v[164:167], v[188:191], v[20:23]
	v_mfma_f32_16x16x32_bf16 v[16:19], v[156:159], v[196:199], v[16:19]
	v_mfma_f32_16x16x32_bf16 v[12:15], v[164:167], v[196:199], v[12:15]
	v_mfma_f32_16x16x32_bf16 v[40:43], v[160:163], v[176:179], v[40:43]
	v_mfma_f32_16x16x32_bf16 v[36:39], v[168:171], v[176:179], v[36:39]
	v_mfma_f32_16x16x32_bf16 v[32:35], v[160:163], v[184:187], v[32:35]
	v_mfma_f32_16x16x32_bf16 v[28:31], v[168:171], v[184:187], v[28:31]
	v_mfma_f32_16x16x32_bf16 v[24:27], v[160:163], v[192:195], v[24:27]
	v_mfma_f32_16x16x32_bf16 v[20:23], v[168:171], v[192:195], v[20:23]
	v_mfma_f32_16x16x32_bf16 v[16:19], v[160:163], v[200:203], v[16:19]
	v_mfma_f32_16x16x32_bf16 v[12:15], v[168:171], v[200:203], v[12:15]
	s_setprio 0
	s_barrier
	s_add_i32 s68, 0, 0x18000
	v_add_u32_e32 v5, s68, v3
	s_add_i32 s70, 0, 0x1c000
	ds_read_b128 v[140:143], v5
	ds_read_b128 v[144:147], v5 offset:1024
	ds_read_b128 v[148:151], v5 offset:2048
	ds_read_b128 v[152:155], v5 offset:3072
	v_add_u32_e32 v5, s70, v3
	ds_read_b128 v[156:159], v5
	ds_read_b128 v[160:163], v5 offset:1024
	ds_read_b128 v[164:167], v5 offset:2048
	ds_read_b128 v[168:171], v5 offset:3072
	s_add_u32 s98, s50, 0x80000
	s_addc_u32 s99, s51, 0
	s_mov_b64 s[100:101], s[50:51]
	s_mov_b32 m0, s49
	ds_read_b128 v[172:175], v246 offset:32768
	ds_read_b128 v[176:179], v246 offset:33792
	ds_read_b128 v[180:183], v246 offset:34816
	ds_read_b128 v[184:187], v246 offset:35840
	ds_read_b128 v[188:191], v246 offset:36864
	ds_read_b128 v[192:195], v246 offset:37888
	ds_read_b128 v[196:199], v246 offset:38912
	ds_read_b128 v[200:203], v246 offset:39936
	global_load_lds_dwordx4 v208, s[98:99]
	s_mov_b32 m0, s52
	s_nop 0
	global_load_lds_dwordx4 v212, s[98:99]
	s_waitcnt vmcnt(8)
	s_waitcnt lgkmcnt(0)
	s_barrier
	s_setprio 1
	s_waitcnt lgkmcnt(0)
	v_mfma_f32_16x16x32_bf16 v[136:139], v[140:143], v[172:175], v[136:139]
	v_mfma_f32_16x16x32_bf16 v[132:135], v[148:151], v[172:175], v[132:135]
	v_mfma_f32_16x16x32_bf16 v[128:131], v[140:143], v[180:183], v[128:131]
	v_mfma_f32_16x16x32_bf16 v[124:127], v[148:151], v[180:183], v[124:127]
	v_mfma_f32_16x16x32_bf16 v[120:123], v[140:143], v[188:191], v[120:123]
	v_mfma_f32_16x16x32_bf16 v[116:119], v[148:151], v[188:191], v[116:119]
	v_mfma_f32_16x16x32_bf16 v[112:115], v[140:143], v[196:199], v[112:115]
	v_mfma_f32_16x16x32_bf16 v[108:111], v[148:151], v[196:199], v[108:111]
	v_mfma_f32_16x16x32_bf16 v[136:139], v[144:147], v[176:179], v[136:139]
	v_mfma_f32_16x16x32_bf16 v[132:135], v[152:155], v[176:179], v[132:135]
	v_mfma_f32_16x16x32_bf16 v[128:131], v[144:147], v[184:187], v[128:131]
	v_mfma_f32_16x16x32_bf16 v[124:127], v[152:155], v[184:187], v[124:127]
	v_mfma_f32_16x16x32_bf16 v[120:123], v[144:147], v[192:195], v[120:123]
	v_mfma_f32_16x16x32_bf16 v[116:119], v[152:155], v[192:195], v[116:119]
	v_mfma_f32_16x16x32_bf16 v[112:115], v[144:147], v[200:203], v[112:115]
	v_mfma_f32_16x16x32_bf16 v[108:111], v[152:155], v[200:203], v[108:111]
	s_setprio 0
	s_setprio 1
	v_mfma_f32_16x16x32_bf16 v[104:107], v[156:159], v[172:175], v[104:107]
	v_mfma_f32_16x16x32_bf16 v[100:103], v[164:167], v[172:175], v[100:103]
	v_mfma_f32_16x16x32_bf16 v[96:99], v[156:159], v[180:183], v[96:99]
	v_mfma_f32_16x16x32_bf16 v[92:95], v[164:167], v[180:183], v[92:95]
	v_mfma_f32_16x16x32_bf16 v[88:91], v[156:159], v[188:191], v[88:91]
	v_mfma_f32_16x16x32_bf16 v[84:87], v[164:167], v[188:191], v[84:87]
	v_mfma_f32_16x16x32_bf16 v[80:83], v[156:159], v[196:199], v[80:83]
	v_mfma_f32_16x16x32_bf16 v[76:79], v[164:167], v[196:199], v[76:79]
	v_mfma_f32_16x16x32_bf16 v[104:107], v[160:163], v[176:179], v[104:107]
	v_mfma_f32_16x16x32_bf16 v[100:103], v[168:171], v[176:179], v[100:103]
	v_mfma_f32_16x16x32_bf16 v[96:99], v[160:163], v[184:187], v[96:99]
	v_mfma_f32_16x16x32_bf16 v[92:95], v[168:171], v[184:187], v[92:95]
	v_mfma_f32_16x16x32_bf16 v[88:91], v[160:163], v[192:195], v[88:91]
	v_mfma_f32_16x16x32_bf16 v[84:87], v[168:171], v[192:195], v[84:87]
	v_mfma_f32_16x16x32_bf16 v[80:83], v[160:163], v[200:203], v[80:83]
	v_mfma_f32_16x16x32_bf16 v[76:79], v[168:171], v[200:203], v[76:79]
	s_setprio 0
	s_barrier
	s_add_i32 s50, s68, s46
	s_add_i32 m0, s50, 0xffffff80
	ds_read_b128 v[172:175], v246 offset:49152
	ds_read_b128 v[176:179], v246 offset:50176
	ds_read_b128 v[180:183], v246 offset:51200
	ds_read_b128 v[184:187], v246 offset:52224
	ds_read_b128 v[188:191], v246 offset:53248
	ds_read_b128 v[192:195], v246 offset:54272
	ds_read_b128 v[196:199], v246 offset:55296
	ds_read_b128 v[200:203], v246 offset:56320
	global_load_lds_dwordx4 v210, s[42:43] offset:128
	s_add_i32 m0, s50, 0x1f80
	s_add_i32 s50, s70, s46
	global_load_lds_dwordx4 v214, s[42:43] offset:128
	s_add_u32 s42, s42, 0x80080
	s_addc_u32 s43, s43, 0
	s_mov_b32 m0, s50
	s_nop 0
	global_load_lds_dwordx4 v210, s[42:43]
	s_add_i32 m0, s50, 0x2000
	s_nop 0
	global_load_lds_dwordx4 v214, s[42:43]
	s_add_i32 m0, s58, 0xffffff80
	s_nop 0
	global_load_lds_dwordx4 v208, s[100:101] offset:128
	s_add_i32 m0, s59, 0xffffff80
	s_nop 0
	global_load_lds_dwordx4 v212, s[100:101] offset:128
	s_waitcnt vmcnt(8)
	s_waitcnt lgkmcnt(0)
	s_barrier
	s_setprio 1
	s_waitcnt lgkmcnt(0)
	v_mfma_f32_16x16x32_bf16 v[72:75], v[140:143], v[172:175], v[72:75]
	v_mfma_f32_16x16x32_bf16 v[68:71], v[148:151], v[172:175], v[68:71]
	v_mfma_f32_16x16x32_bf16 v[64:67], v[140:143], v[180:183], v[64:67]
	v_mfma_f32_16x16x32_bf16 v[60:63], v[148:151], v[180:183], v[60:63]
	v_mfma_f32_16x16x32_bf16 v[56:59], v[140:143], v[188:191], v[56:59]
	v_mfma_f32_16x16x32_bf16 v[52:55], v[148:151], v[188:191], v[52:55]
	v_mfma_f32_16x16x32_bf16 v[48:51], v[140:143], v[196:199], v[48:51]
	v_mfma_f32_16x16x32_bf16 v[44:47], v[148:151], v[196:199], v[44:47]
	v_mfma_f32_16x16x32_bf16 v[72:75], v[144:147], v[176:179], v[72:75]
	v_mfma_f32_16x16x32_bf16 v[68:71], v[152:155], v[176:179], v[68:71]
	v_mfma_f32_16x16x32_bf16 v[64:67], v[144:147], v[184:187], v[64:67]
	v_mfma_f32_16x16x32_bf16 v[60:63], v[152:155], v[184:187], v[60:63]
	v_mfma_f32_16x16x32_bf16 v[56:59], v[144:147], v[192:195], v[56:59]
	v_mfma_f32_16x16x32_bf16 v[52:55], v[152:155], v[192:195], v[52:55]
	v_mfma_f32_16x16x32_bf16 v[48:51], v[144:147], v[200:203], v[48:51]
	v_mfma_f32_16x16x32_bf16 v[44:47], v[152:155], v[200:203], v[44:47]
	s_setprio 0
	s_setprio 1
	v_mfma_f32_16x16x32_bf16 v[40:43], v[156:159], v[172:175], v[40:43]
	v_mfma_f32_16x16x32_bf16 v[36:39], v[164:167], v[172:175], v[36:39]
	v_mfma_f32_16x16x32_bf16 v[32:35], v[156:159], v[180:183], v[32:35]
	v_mfma_f32_16x16x32_bf16 v[28:31], v[164:167], v[180:183], v[28:31]
	v_mfma_f32_16x16x32_bf16 v[24:27], v[156:159], v[188:191], v[24:27]
	v_mfma_f32_16x16x32_bf16 v[20:23], v[164:167], v[188:191], v[20:23]
	v_mfma_f32_16x16x32_bf16 v[16:19], v[156:159], v[196:199], v[16:19]
	v_mfma_f32_16x16x32_bf16 v[12:15], v[164:167], v[196:199], v[12:15]
	v_mfma_f32_16x16x32_bf16 v[40:43], v[160:163], v[176:179], v[40:43]
	v_mfma_f32_16x16x32_bf16 v[36:39], v[168:171], v[176:179], v[36:39]
	v_mfma_f32_16x16x32_bf16 v[32:35], v[160:163], v[184:187], v[32:35]
	v_mfma_f32_16x16x32_bf16 v[28:31], v[168:171], v[184:187], v[28:31]
	v_mfma_f32_16x16x32_bf16 v[24:27], v[160:163], v[192:195], v[24:27]
	v_mfma_f32_16x16x32_bf16 v[20:23], v[168:171], v[192:195], v[20:23]
	v_mfma_f32_16x16x32_bf16 v[16:19], v[160:163], v[200:203], v[16:19]
	v_mfma_f32_16x16x32_bf16 v[12:15], v[168:171], v[200:203], v[12:15]
	s_setprio 0
	s_barrier
	s_add_i32 s67, s67, 2
	s_add_u32 s40, s40, 0x100
	s_addc_u32 s41, s41, 0
	s_add_u32 s65, s65, 0x100
	s_addc_u32 s66, s66, 0
	s_cmp_gt_u32 s67, 29
	s_cbranch_scc0 .LBB0_1032
	s_and_b64 vcc, exec, s[22:23]
	s_cbranch_vccz .LBB0_1035
	s_barrier

.LBB0_1203:
	ds_read_b128 v[132:135], v187
	ds_read_b128 v[136:139], v187 offset:1024
	ds_read_b128 v[140:143], v187 offset:2048
	ds_read_b128 v[144:147], v187 offset:3072
	ds_read_b128 v[148:151], v188
	ds_read_b128 v[152:155], v188 offset:1024
	ds_read_b128 v[172:175], v188 offset:2048
	ds_read_b128 v[176:179], v188 offset:3072
	s_add_u32 s0, s42, 0xfff00080
	s_addc_u32 s50, s43, -1
	s_cmp_eq_u32 s65, 60
	s_cselect_b32 s53, s25, s50
	s_cselect_b32 s52, s31, s0
	s_cselect_b32 s51, s23, s64
	s_cselect_b32 s50, s62, s63
	s_add_i32 m0, s41, 0xc000
	ds_read_b128 v[180:183], v189
	ds_read_b128 v[192:195], v189 offset:1024
	ds_read_b128 v[196:199], v189 offset:2048
	ds_read_b128 v[200:203], v189 offset:3072
	ds_read_b128 v[204:207], v189 offset:4096
	ds_read_b128 v[208:211], v189 offset:5120
	ds_read_b128 v[212:215], v189 offset:6144
	ds_read_b128 v[216:219], v189 offset:7168
	global_load_lds_dwordx4 v164, s[42:43]
	s_add_i32 m0, s41, 0xe000
	s_nop 0
	global_load_lds_dwordx4 v166, s[42:43]
	s_waitcnt vmcnt(8)
	s_waitcnt lgkmcnt(0)
	s_barrier
	s_setprio 1
	s_waitcnt lgkmcnt(0)
	v_mfma_f32_16x16x32_bf16 v[128:131], v[132:135], v[180:183], v[128:131]
	v_mfma_f32_16x16x32_bf16 v[124:127], v[140:143], v[180:183], v[124:127]
	v_mfma_f32_16x16x32_bf16 v[112:115], v[132:135], v[196:199], v[112:115]
	v_mfma_f32_16x16x32_bf16 v[108:111], v[140:143], v[196:199], v[108:111]
	v_mfma_f32_16x16x32_bf16 v[96:99], v[132:135], v[204:207], v[96:99]
	v_mfma_f32_16x16x32_bf16 v[92:95], v[140:143], v[204:207], v[92:95]
	v_mfma_f32_16x16x32_bf16 v[80:83], v[132:135], v[212:215], v[80:83]
	v_mfma_f32_16x16x32_bf16 v[76:79], v[140:143], v[212:215], v[76:79]
	v_mfma_f32_16x16x32_bf16 v[128:131], v[136:139], v[192:195], v[128:131]
	v_mfma_f32_16x16x32_bf16 v[124:127], v[144:147], v[192:195], v[124:127]
	v_mfma_f32_16x16x32_bf16 v[112:115], v[136:139], v[200:203], v[112:115]
	v_mfma_f32_16x16x32_bf16 v[108:111], v[144:147], v[200:203], v[108:111]
	v_mfma_f32_16x16x32_bf16 v[96:99], v[136:139], v[208:211], v[96:99]
	v_mfma_f32_16x16x32_bf16 v[92:95], v[144:147], v[208:211], v[92:95]
	v_mfma_f32_16x16x32_bf16 v[80:83], v[136:139], v[216:219], v[80:83]
	v_mfma_f32_16x16x32_bf16 v[76:79], v[144:147], v[216:219], v[76:79]
	s_setprio 0
	s_setprio 1
	v_mfma_f32_16x16x32_bf16 v[120:123], v[148:151], v[180:183], v[120:123]
	v_mfma_f32_16x16x32_bf16 v[116:119], v[172:175], v[180:183], v[116:119]
	v_mfma_f32_16x16x32_bf16 v[104:107], v[148:151], v[196:199], v[104:107]
	v_mfma_f32_16x16x32_bf16 v[100:103], v[172:175], v[196:199], v[100:103]
	v_mfma_f32_16x16x32_bf16 v[88:91], v[148:151], v[204:207], v[88:91]
	v_mfma_f32_16x16x32_bf16 v[84:87], v[172:175], v[204:207], v[84:87]
	v_mfma_f32_16x16x32_bf16 v[72:75], v[148:151], v[212:215], v[72:75]
	v_mfma_f32_16x16x32_bf16 v[68:71], v[172:175], v[212:215], v[68:71]
	v_mfma_f32_16x16x32_bf16 v[120:123], v[152:155], v[192:195], v[120:123]
	v_mfma_f32_16x16x32_bf16 v[116:119], v[176:179], v[192:195], v[116:119]
	v_mfma_f32_16x16x32_bf16 v[104:107], v[152:155], v[200:203], v[104:107]
	v_mfma_f32_16x16x32_bf16 v[100:103], v[176:179], v[200:203], v[100:103]
	v_mfma_f32_16x16x32_bf16 v[88:91], v[152:155], v[208:211], v[88:91]
	v_mfma_f32_16x16x32_bf16 v[84:87], v[176:179], v[208:211], v[84:87]
	v_mfma_f32_16x16x32_bf16 v[72:75], v[152:155], v[216:219], v[72:75]
	v_mfma_f32_16x16x32_bf16 v[68:71], v[176:179], v[216:219], v[68:71]
	s_setprio 0
	s_barrier
	s_add_i32 s0, s59, s46
	s_mov_b32 m0, s0
	ds_read_b128 v[180:183], v189 offset:16384
	ds_read_b128 v[192:195], v189 offset:17408
	ds_read_b128 v[196:199], v189 offset:18432
	ds_read_b128 v[200:203], v189 offset:19456
	ds_read_b128 v[204:207], v189 offset:20480
	ds_read_b128 v[208:211], v189 offset:21504
	ds_read_b128 v[212:215], v189 offset:22528
	ds_read_b128 v[216:219], v189 offset:23552
	global_load_lds_dwordx4 v158, s[50:51]
	s_add_i32 m0, s0, 0x2000
	s_add_u32 s66, s50, 0x100000
	s_addc_u32 s67, s51, 0
	s_add_i32 s0, s60, s46
	global_load_lds_dwordx4 v162, s[50:51]
	s_mov_b32 m0, s0
	s_nop 0
	global_load_lds_dwordx4 v158, s[66:67]
	s_add_i32 m0, s0, 0x2000
	s_nop 0
	global_load_lds_dwordx4 v162, s[66:67]
	s_mov_b32 m0, s41
	s_nop 0
	global_load_lds_dwordx4 v156, s[52:53]
	s_mov_b32 m0, s47
	s_nop 0
	global_load_lds_dwordx4 v160, s[52:53]
	s_waitcnt vmcnt(8)
	s_waitcnt lgkmcnt(0)
	s_barrier
	s_setprio 1
	s_waitcnt lgkmcnt(0)
	v_mfma_f32_16x16x32_bf16 v[64:67], v[132:135], v[180:183], v[64:67]
	v_mfma_f32_16x16x32_bf16 v[60:63], v[140:143], v[180:183], v[60:63]
	v_mfma_f32_16x16x32_bf16 v[48:51], v[132:135], v[196:199], v[48:51]
	v_mfma_f32_16x16x32_bf16 v[44:47], v[140:143], v[196:199], v[44:47]
	v_mfma_f32_16x16x32_bf16 v[32:35], v[132:135], v[204:207], v[32:35]
	v_mfma_f32_16x16x32_bf16 v[28:31], v[140:143], v[204:207], v[28:31]
	v_mfma_f32_16x16x32_bf16 v[16:19], v[132:135], v[212:215], v[16:19]
	v_mfma_f32_16x16x32_bf16 v[12:15], v[140:143], v[212:215], v[12:15]
	v_mfma_f32_16x16x32_bf16 v[64:67], v[136:139], v[192:195], v[64:67]
	v_mfma_f32_16x16x32_bf16 v[60:63], v[144:147], v[192:195], v[60:63]
	v_mfma_f32_16x16x32_bf16 v[48:51], v[136:139], v[200:203], v[48:51]
	v_mfma_f32_16x16x32_bf16 v[44:47], v[144:147], v[200:203], v[44:47]
	v_mfma_f32_16x16x32_bf16 v[32:35], v[136:139], v[208:211], v[32:35]
	v_mfma_f32_16x16x32_bf16 v[28:31], v[144:147], v[208:211], v[28:31]
	v_mfma_f32_16x16x32_bf16 v[16:19], v[136:139], v[216:219], v[16:19]
	v_mfma_f32_16x16x32_bf16 v[12:15], v[144:147], v[216:219], v[12:15]
	s_setprio 0
	s_setprio 1
	v_mfma_f32_16x16x32_bf16 v[56:59], v[148:151], v[180:183], v[56:59]
	v_mfma_f32_16x16x32_bf16 v[52:55], v[172:175], v[180:183], v[52:55]
	v_mfma_f32_16x16x32_bf16 v[40:43], v[148:151], v[196:199], v[40:43]
	v_mfma_f32_16x16x32_bf16 v[36:39], v[172:175], v[196:199], v[36:39]
	v_mfma_f32_16x16x32_bf16 v[24:27], v[148:151], v[204:207], v[24:27]
	v_mfma_f32_16x16x32_bf16 v[20:23], v[172:175], v[204:207], v[20:23]
	v_mfma_f32_16x16x32_bf16 v[8:11], v[148:151], v[212:215], v[8:11]
	v_mfma_f32_16x16x32_bf16 v[4:7], v[172:175], v[212:215], v[4:7]
	v_mfma_f32_16x16x32_bf16 v[56:59], v[152:155], v[192:195], v[56:59]
	v_mfma_f32_16x16x32_bf16 v[52:55], v[176:179], v[192:195], v[52:55]
	v_mfma_f32_16x16x32_bf16 v[40:43], v[152:155], v[200:203], v[40:43]
	v_mfma_f32_16x16x32_bf16 v[36:39], v[176:179], v[200:203], v[36:39]
	v_mfma_f32_16x16x32_bf16 v[24:27], v[152:155], v[208:211], v[24:27]
	v_mfma_f32_16x16x32_bf16 v[20:23], v[176:179], v[208:211], v[20:23]
	v_mfma_f32_16x16x32_bf16 v[8:11], v[152:155], v[216:219], v[8:11]
	v_mfma_f32_16x16x32_bf16 v[4:7], v[176:179], v[216:219], v[4:7]
	s_setprio 0
	s_barrier
	s_add_i32 s0, 0, 0x18000
	s_add_i32 s66, 0, 0x1c000
	v_add_u32_e32 v144, s0, v3
	v_add_u32_e32 v176, s66, v3
	ds_read_b128 v[132:135], v144
	ds_read_b128 v[136:139], v144 offset:1024
	ds_read_b128 v[140:143], v144 offset:2048
	ds_read_b128 v[144:147], v144 offset:3072
	ds_read_b128 v[148:151], v176
	ds_read_b128 v[152:155], v176 offset:1024
	ds_read_b128 v[172:175], v176 offset:2048
	ds_read_b128 v[176:179], v176 offset:3072
	s_add_u32 s98, s52, 0x100000
	s_addc_u32 s99, s53, 0
	s_mov_b32 m0, s48
	ds_read_b128 v[180:183], v189 offset:32768
	ds_read_b128 v[192:195], v189 offset:33792
	ds_read_b128 v[196:199], v189 offset:34816
	ds_read_b128 v[200:203], v189 offset:35840
	ds_read_b128 v[204:207], v189 offset:36864
	ds_read_b128 v[208:211], v189 offset:37888
	ds_read_b128 v[212:215], v189 offset:38912
	ds_read_b128 v[216:219], v189 offset:39936
	global_load_lds_dwordx4 v156, s[98:99]
	s_mov_b32 m0, s49
	s_nop 0
	global_load_lds_dwordx4 v160, s[98:99]
	s_waitcnt vmcnt(8)
	s_waitcnt lgkmcnt(0)
	s_barrier
	s_setprio 1
	s_waitcnt lgkmcnt(0)
	v_mfma_f32_16x16x32_bf16 v[128:131], v[132:135], v[180:183], v[128:131]
	v_mfma_f32_16x16x32_bf16 v[124:127], v[140:143], v[180:183], v[124:127]
	v_mfma_f32_16x16x32_bf16 v[112:115], v[132:135], v[196:199], v[112:115]
	v_mfma_f32_16x16x32_bf16 v[108:111], v[140:143], v[196:199], v[108:111]
	v_mfma_f32_16x16x32_bf16 v[96:99], v[132:135], v[204:207], v[96:99]
	v_mfma_f32_16x16x32_bf16 v[92:95], v[140:143], v[204:207], v[92:95]
	v_mfma_f32_16x16x32_bf16 v[80:83], v[132:135], v[212:215], v[80:83]
	v_mfma_f32_16x16x32_bf16 v[76:79], v[140:143], v[212:215], v[76:79]
	v_mfma_f32_16x16x32_bf16 v[128:131], v[136:139], v[192:195], v[128:131]
	v_mfma_f32_16x16x32_bf16 v[124:127], v[144:147], v[192:195], v[124:127]
	v_mfma_f32_16x16x32_bf16 v[112:115], v[136:139], v[200:203], v[112:115]
	v_mfma_f32_16x16x32_bf16 v[108:111], v[144:147], v[200:203], v[108:111]
	v_mfma_f32_16x16x32_bf16 v[96:99], v[136:139], v[208:211], v[96:99]
	v_mfma_f32_16x16x32_bf16 v[92:95], v[144:147], v[208:211], v[92:95]
	v_mfma_f32_16x16x32_bf16 v[80:83], v[136:139], v[216:219], v[80:83]
	v_mfma_f32_16x16x32_bf16 v[76:79], v[144:147], v[216:219], v[76:79]
	s_setprio 0
	s_setprio 1
	v_mfma_f32_16x16x32_bf16 v[120:123], v[148:151], v[180:183], v[120:123]
	v_mfma_f32_16x16x32_bf16 v[116:119], v[172:175], v[180:183], v[116:119]
	v_mfma_f32_16x16x32_bf16 v[104:107], v[148:151], v[196:199], v[104:107]
	v_mfma_f32_16x16x32_bf16 v[100:103], v[172:175], v[196:199], v[100:103]
	v_mfma_f32_16x16x32_bf16 v[88:91], v[148:151], v[204:207], v[88:91]
	v_mfma_f32_16x16x32_bf16 v[84:87], v[172:175], v[204:207], v[84:87]
	v_mfma_f32_16x16x32_bf16 v[72:75], v[148:151], v[212:215], v[72:75]
	v_mfma_f32_16x16x32_bf16 v[68:71], v[172:175], v[212:215], v[68:71]
	v_mfma_f32_16x16x32_bf16 v[120:123], v[152:155], v[192:195], v[120:123]
	v_mfma_f32_16x16x32_bf16 v[116:119], v[176:179], v[192:195], v[116:119]
	v_mfma_f32_16x16x32_bf16 v[104:107], v[152:155], v[200:203], v[104:107]
	v_mfma_f32_16x16x32_bf16 v[100:103], v[176:179], v[200:203], v[100:103]
	v_mfma_f32_16x16x32_bf16 v[88:91], v[152:155], v[208:211], v[88:91]
	v_mfma_f32_16x16x32_bf16 v[84:87], v[176:179], v[208:211], v[84:87]
	v_mfma_f32_16x16x32_bf16 v[72:75], v[152:155], v[216:219], v[72:75]
	v_mfma_f32_16x16x32_bf16 v[68:71], v[176:179], v[216:219], v[68:71]
	s_setprio 0
	s_barrier
	s_add_i32 s0, s0, s46
	s_add_i32 m0, s0, 0xffffff80
	ds_read_b128 v[180:183], v189 offset:49152
	ds_read_b128 v[192:195], v189 offset:50176
	ds_read_b128 v[196:199], v189 offset:51200
	ds_read_b128 v[200:203], v189 offset:52224
	ds_read_b128 v[204:207], v189 offset:53248
	ds_read_b128 v[208:211], v189 offset:54272
	ds_read_b128 v[212:215], v189 offset:55296
	ds_read_b128 v[216:219], v189 offset:56320
	global_load_lds_dwordx4 v158, s[50:51] offset:128
	s_add_i32 m0, s0, 0x1f80
	s_add_i32 s0, s66, s46
	global_load_lds_dwordx4 v162, s[50:51] offset:128
	s_add_u32 s50, s50, 0x100080
	s_addc_u32 s51, s51, 0
	s_mov_b32 m0, s0
	s_nop 0
	global_load_lds_dwordx4 v158, s[50:51]
	s_add_i32 m0, s0, 0x2000
	s_nop 0
	global_load_lds_dwordx4 v162, s[50:51]
	s_add_i32 m0, s57, 0xffffff80
	s_nop 0
	global_load_lds_dwordx4 v156, s[52:53] offset:128
	s_add_i32 m0, s58, 0xffffff80
	s_nop 0
	global_load_lds_dwordx4 v160, s[52:53] offset:128
	s_waitcnt vmcnt(8)
	s_waitcnt lgkmcnt(0)
	s_barrier
	s_setprio 1
	s_waitcnt lgkmcnt(0)
	v_mfma_f32_16x16x32_bf16 v[64:67], v[132:135], v[180:183], v[64:67]
	v_mfma_f32_16x16x32_bf16 v[60:63], v[140:143], v[180:183], v[60:63]
	v_mfma_f32_16x16x32_bf16 v[48:51], v[132:135], v[196:199], v[48:51]
	v_mfma_f32_16x16x32_bf16 v[44:47], v[140:143], v[196:199], v[44:47]
	v_mfma_f32_16x16x32_bf16 v[32:35], v[132:135], v[204:207], v[32:35]
	v_mfma_f32_16x16x32_bf16 v[28:31], v[140:143], v[204:207], v[28:31]
	v_mfma_f32_16x16x32_bf16 v[16:19], v[132:135], v[212:215], v[16:19]
	v_mfma_f32_16x16x32_bf16 v[12:15], v[140:143], v[212:215], v[12:15]
	v_mfma_f32_16x16x32_bf16 v[64:67], v[136:139], v[192:195], v[64:67]
	v_mfma_f32_16x16x32_bf16 v[60:63], v[144:147], v[192:195], v[60:63]
	v_mfma_f32_16x16x32_bf16 v[48:51], v[136:139], v[200:203], v[48:51]
	v_mfma_f32_16x16x32_bf16 v[44:47], v[144:147], v[200:203], v[44:47]
	v_mfma_f32_16x16x32_bf16 v[32:35], v[136:139], v[208:211], v[32:35]
	v_mfma_f32_16x16x32_bf16 v[28:31], v[144:147], v[208:211], v[28:31]
	v_mfma_f32_16x16x32_bf16 v[16:19], v[136:139], v[216:219], v[16:19]
	v_mfma_f32_16x16x32_bf16 v[12:15], v[144:147], v[216:219], v[12:15]
	s_setprio 0
	s_setprio 1
	v_mfma_f32_16x16x32_bf16 v[56:59], v[148:151], v[180:183], v[56:59]
	v_mfma_f32_16x16x32_bf16 v[52:55], v[172:175], v[180:183], v[52:55]
	v_mfma_f32_16x16x32_bf16 v[40:43], v[148:151], v[196:199], v[40:43]
	v_mfma_f32_16x16x32_bf16 v[36:39], v[172:175], v[196:199], v[36:39]
	v_mfma_f32_16x16x32_bf16 v[24:27], v[148:151], v[204:207], v[24:27]
	v_mfma_f32_16x16x32_bf16 v[20:23], v[172:175], v[204:207], v[20:23]
	v_mfma_f32_16x16x32_bf16 v[8:11], v[148:151], v[212:215], v[8:11]
	v_mfma_f32_16x16x32_bf16 v[4:7], v[172:175], v[212:215], v[4:7]
	v_mfma_f32_16x16x32_bf16 v[56:59], v[152:155], v[192:195], v[56:59]
	v_mfma_f32_16x16x32_bf16 v[52:55], v[176:179], v[192:195], v[52:55]
	v_mfma_f32_16x16x32_bf16 v[40:43], v[152:155], v[200:203], v[40:43]
	v_mfma_f32_16x16x32_bf16 v[36:39], v[176:179], v[200:203], v[36:39]
	v_mfma_f32_16x16x32_bf16 v[24:27], v[152:155], v[208:211], v[24:27]
	v_mfma_f32_16x16x32_bf16 v[20:23], v[176:179], v[208:211], v[20:23]
	v_mfma_f32_16x16x32_bf16 v[8:11], v[152:155], v[216:219], v[8:11]
	v_mfma_f32_16x16x32_bf16 v[4:7], v[176:179], v[216:219], v[4:7]
	s_setprio 0
	s_barrier
	s_add_i32 s65, s65, 2
	s_add_u32 s42, s42, 0x100
	s_addc_u32 s43, s43, 0
	s_add_u32 s63, s63, 0x100
	s_addc_u32 s64, s64, 0
	s_cmp_gt_u32 s65, 61
	s_cbranch_scc0 .LBB0_1203
	s_and_b64 vcc, exec, s[20:21]
	s_cbranch_vccz .LBB0_1206
	s_barrier

.LBB0_1288:
	ds_read_b128 v[154:157], v150
	ds_read_b128 v[158:161], v150 offset:1024
	ds_read_b128 v[162:165], v150 offset:2048
	ds_read_b128 v[166:169], v150 offset:3072
	ds_read_b128 v[170:173], v151
	ds_read_b128 v[174:177], v151 offset:1024
	ds_read_b128 v[178:181], v151 offset:2048
	ds_read_b128 v[182:185], v151 offset:3072
	s_add_u32 s0, s42, 0xfff00080
	s_addc_u32 s50, s43, -1
	s_cmp_eq_u32 s70, 12
	s_cselect_b32 s53, s29, s50
	s_cselect_b32 s52, s28, s0
	s_cselect_b32 s51, s5, s41
	s_cselect_b32 s50, s4, s31
	s_add_i32 m0, s17, 0xc000
	ds_read_b128 v[186:189], v152
	ds_read_b128 v[190:193], v152 offset:1024
	ds_read_b128 v[194:197], v152 offset:2048
	ds_read_b128 v[198:201], v152 offset:3072
	ds_read_b128 v[202:205], v152 offset:4096
	ds_read_b128 v[206:209], v152 offset:5120
	ds_read_b128 v[210:213], v152 offset:6144
	ds_read_b128 v[214:217], v152 offset:7168
	global_load_lds_dwordx4 v142, s[42:43]
	s_add_i32 m0, s17, 0xe000
	s_nop 0
	global_load_lds_dwordx4 v144, s[42:43]
	s_waitcnt vmcnt(8)
	s_waitcnt lgkmcnt(0)
	s_barrier
	s_setprio 1
	s_waitcnt lgkmcnt(0)
	v_mfma_f32_16x16x32_bf16 v[128:131], v[154:157], v[186:189], v[128:131]
	v_mfma_f32_16x16x32_bf16 v[124:127], v[162:165], v[186:189], v[124:127]
	v_mfma_f32_16x16x32_bf16 v[120:123], v[154:157], v[194:197], v[120:123]
	v_mfma_f32_16x16x32_bf16 v[116:119], v[162:165], v[194:197], v[116:119]
	v_mfma_f32_16x16x32_bf16 v[104:107], v[154:157], v[202:205], v[104:107]
	v_mfma_f32_16x16x32_bf16 v[100:103], v[162:165], v[202:205], v[100:103]
	v_mfma_f32_16x16x32_bf16 v[88:91], v[154:157], v[210:213], v[88:91]
	v_mfma_f32_16x16x32_bf16 v[84:87], v[162:165], v[210:213], v[84:87]
	v_mfma_f32_16x16x32_bf16 v[128:131], v[158:161], v[190:193], v[128:131]
	v_mfma_f32_16x16x32_bf16 v[124:127], v[166:169], v[190:193], v[124:127]
	v_mfma_f32_16x16x32_bf16 v[120:123], v[158:161], v[198:201], v[120:123]
	v_mfma_f32_16x16x32_bf16 v[116:119], v[166:169], v[198:201], v[116:119]
	v_mfma_f32_16x16x32_bf16 v[104:107], v[158:161], v[206:209], v[104:107]
	v_mfma_f32_16x16x32_bf16 v[100:103], v[166:169], v[206:209], v[100:103]
	v_mfma_f32_16x16x32_bf16 v[88:91], v[158:161], v[214:217], v[88:91]
	v_mfma_f32_16x16x32_bf16 v[84:87], v[166:169], v[214:217], v[84:87]
	s_setprio 0
	s_setprio 1
	v_mfma_f32_16x16x32_bf16 v[112:115], v[170:173], v[186:189], v[112:115]
	v_mfma_f32_16x16x32_bf16 v[108:111], v[178:181], v[186:189], v[108:111]
	v_mfma_f32_16x16x32_bf16 v[96:99], v[170:173], v[194:197], v[96:99]
	v_mfma_f32_16x16x32_bf16 v[92:95], v[178:181], v[194:197], v[92:95]
	v_mfma_f32_16x16x32_bf16 v[80:83], v[170:173], v[202:205], v[80:83]
	v_mfma_f32_16x16x32_bf16 v[76:79], v[178:181], v[202:205], v[76:79]
	v_mfma_f32_16x16x32_bf16 v[72:75], v[170:173], v[210:213], v[72:75]
	v_mfma_f32_16x16x32_bf16 v[68:71], v[178:181], v[210:213], v[68:71]
	v_mfma_f32_16x16x32_bf16 v[112:115], v[174:177], v[190:193], v[112:115]
	v_mfma_f32_16x16x32_bf16 v[108:111], v[182:185], v[190:193], v[108:111]
	v_mfma_f32_16x16x32_bf16 v[96:99], v[174:177], v[198:201], v[96:99]
	v_mfma_f32_16x16x32_bf16 v[92:95], v[182:185], v[198:201], v[92:95]
	v_mfma_f32_16x16x32_bf16 v[80:83], v[174:177], v[206:209], v[80:83]
	v_mfma_f32_16x16x32_bf16 v[76:79], v[182:185], v[206:209], v[76:79]
	v_mfma_f32_16x16x32_bf16 v[72:75], v[174:177], v[214:217], v[72:75]
	v_mfma_f32_16x16x32_bf16 v[68:71], v[182:185], v[214:217], v[68:71]
	s_setprio 0
	s_barrier
	s_add_i32 s0, s60, s46
	s_mov_b32 m0, s0
	ds_read_b128 v[186:189], v152 offset:16384
	ds_read_b128 v[190:193], v152 offset:17408
	ds_read_b128 v[194:197], v152 offset:18432
	ds_read_b128 v[198:201], v152 offset:19456
	ds_read_b128 v[202:205], v152 offset:20480
	ds_read_b128 v[206:209], v152 offset:21504
	ds_read_b128 v[210:213], v152 offset:22528
	ds_read_b128 v[214:217], v152 offset:23552
	global_load_lds_dwordx4 v136, s[50:51]
	s_add_i32 m0, s0, 0x2000
	s_add_u32 s72, s50, 0x100000
	s_addc_u32 s73, s51, 0
	s_add_i32 s0, s61, s46
	global_load_lds_dwordx4 v132, s[50:51]
	s_mov_b32 m0, s0
	s_nop 0
	global_load_lds_dwordx4 v136, s[72:73]
	s_add_i32 m0, s0, 0x2000
	s_nop 0
	global_load_lds_dwordx4 v132, s[72:73]
	s_mov_b32 m0, s17
	s_nop 0
	global_load_lds_dwordx4 v138, s[52:53]
	s_mov_b32 m0, s47
	s_nop 0
	global_load_lds_dwordx4 v134, s[52:53]
	s_waitcnt vmcnt(8)
	s_waitcnt lgkmcnt(0)
	s_barrier
	s_setprio 1
	s_waitcnt lgkmcnt(0)
	v_mfma_f32_16x16x32_bf16 v[64:67], v[154:157], v[186:189], v[64:67]
	v_mfma_f32_16x16x32_bf16 v[60:63], v[162:165], v[186:189], v[60:63]
	v_mfma_f32_16x16x32_bf16 v[56:59], v[154:157], v[194:197], v[56:59]
	v_mfma_f32_16x16x32_bf16 v[52:55], v[162:165], v[194:197], v[52:55]
	v_mfma_f32_16x16x32_bf16 v[40:43], v[154:157], v[202:205], v[40:43]
	v_mfma_f32_16x16x32_bf16 v[36:39], v[162:165], v[202:205], v[36:39]
	v_mfma_f32_16x16x32_bf16 v[24:27], v[154:157], v[210:213], v[24:27]
	v_mfma_f32_16x16x32_bf16 v[20:23], v[162:165], v[210:213], v[20:23]
	v_mfma_f32_16x16x32_bf16 v[64:67], v[158:161], v[190:193], v[64:67]
	v_mfma_f32_16x16x32_bf16 v[60:63], v[166:169], v[190:193], v[60:63]
	v_mfma_f32_16x16x32_bf16 v[56:59], v[158:161], v[198:201], v[56:59]
	v_mfma_f32_16x16x32_bf16 v[52:55], v[166:169], v[198:201], v[52:55]
	v_mfma_f32_16x16x32_bf16 v[40:43], v[158:161], v[206:209], v[40:43]
	v_mfma_f32_16x16x32_bf16 v[36:39], v[166:169], v[206:209], v[36:39]
	v_mfma_f32_16x16x32_bf16 v[24:27], v[158:161], v[214:217], v[24:27]
	v_mfma_f32_16x16x32_bf16 v[20:23], v[166:169], v[214:217], v[20:23]
	s_setprio 0
	s_setprio 1
	v_mfma_f32_16x16x32_bf16 v[48:51], v[170:173], v[186:189], v[48:51]
	v_mfma_f32_16x16x32_bf16 v[44:47], v[178:181], v[186:189], v[44:47]
	v_mfma_f32_16x16x32_bf16 v[32:35], v[170:173], v[194:197], v[32:35]
	v_mfma_f32_16x16x32_bf16 v[28:31], v[178:181], v[194:197], v[28:31]
	v_mfma_f32_16x16x32_bf16 v[16:19], v[170:173], v[202:205], v[16:19]
	v_mfma_f32_16x16x32_bf16 v[12:15], v[178:181], v[202:205], v[12:15]
	v_mfma_f32_16x16x32_bf16 v[8:11], v[170:173], v[210:213], v[8:11]
	v_mfma_f32_16x16x32_bf16 v[4:7], v[178:181], v[210:213], v[4:7]
	v_mfma_f32_16x16x32_bf16 v[48:51], v[174:177], v[190:193], v[48:51]
	v_mfma_f32_16x16x32_bf16 v[44:47], v[182:185], v[190:193], v[44:47]
	v_mfma_f32_16x16x32_bf16 v[32:35], v[174:177], v[198:201], v[32:35]
	v_mfma_f32_16x16x32_bf16 v[28:31], v[182:185], v[198:201], v[28:31]
	v_mfma_f32_16x16x32_bf16 v[16:19], v[174:177], v[206:209], v[16:19]
	v_mfma_f32_16x16x32_bf16 v[12:15], v[182:185], v[206:209], v[12:15]
	v_mfma_f32_16x16x32_bf16 v[8:11], v[174:177], v[214:217], v[8:11]
	v_mfma_f32_16x16x32_bf16 v[4:7], v[182:185], v[214:217], v[4:7]
	s_setprio 0
	s_barrier
	s_add_i32 s0, 0, 0x18000
	v_add_u32_e32 v140, s0, v3
	s_add_i32 s71, 0, 0x1c000
	ds_read_b128 v[154:157], v140
	ds_read_b128 v[158:161], v140 offset:1024
	ds_read_b128 v[162:165], v140 offset:2048
	ds_read_b128 v[166:169], v140 offset:3072
	v_add_u32_e32 v140, s71, v3
	ds_read_b128 v[170:173], v140
	ds_read_b128 v[174:177], v140 offset:1024
	ds_read_b128 v[178:181], v140 offset:2048
	ds_read_b128 v[182:185], v140 offset:3072
	s_add_u32 s98, s52, 0x100000
	s_addc_u32 s99, s53, 0
	s_mov_b32 m0, s48
	ds_read_b128 v[186:189], v152 offset:32768
	ds_read_b128 v[190:193], v152 offset:33792
	ds_read_b128 v[194:197], v152 offset:34816
	ds_read_b128 v[198:201], v152 offset:35840
	ds_read_b128 v[202:205], v152 offset:36864
	ds_read_b128 v[206:209], v152 offset:37888
	ds_read_b128 v[210:213], v152 offset:38912
	ds_read_b128 v[214:217], v152 offset:39936
	global_load_lds_dwordx4 v138, s[98:99]
	s_mov_b32 m0, s49
	s_nop 0
	global_load_lds_dwordx4 v134, s[98:99]
	s_waitcnt vmcnt(8)
	s_waitcnt lgkmcnt(0)
	s_barrier
	s_setprio 1
	s_waitcnt lgkmcnt(0)
	v_mfma_f32_16x16x32_bf16 v[128:131], v[154:157], v[186:189], v[128:131]
	v_mfma_f32_16x16x32_bf16 v[124:127], v[162:165], v[186:189], v[124:127]
	v_mfma_f32_16x16x32_bf16 v[120:123], v[154:157], v[194:197], v[120:123]
	v_mfma_f32_16x16x32_bf16 v[116:119], v[162:165], v[194:197], v[116:119]
	v_mfma_f32_16x16x32_bf16 v[104:107], v[154:157], v[202:205], v[104:107]
	v_mfma_f32_16x16x32_bf16 v[100:103], v[162:165], v[202:205], v[100:103]
	v_mfma_f32_16x16x32_bf16 v[88:91], v[154:157], v[210:213], v[88:91]
	v_mfma_f32_16x16x32_bf16 v[84:87], v[162:165], v[210:213], v[84:87]
	v_mfma_f32_16x16x32_bf16 v[128:131], v[158:161], v[190:193], v[128:131]
	v_mfma_f32_16x16x32_bf16 v[124:127], v[166:169], v[190:193], v[124:127]
	v_mfma_f32_16x16x32_bf16 v[120:123], v[158:161], v[198:201], v[120:123]
	v_mfma_f32_16x16x32_bf16 v[116:119], v[166:169], v[198:201], v[116:119]
	v_mfma_f32_16x16x32_bf16 v[104:107], v[158:161], v[206:209], v[104:107]
	v_mfma_f32_16x16x32_bf16 v[100:103], v[166:169], v[206:209], v[100:103]
	v_mfma_f32_16x16x32_bf16 v[88:91], v[158:161], v[214:217], v[88:91]
	v_mfma_f32_16x16x32_bf16 v[84:87], v[166:169], v[214:217], v[84:87]
	s_setprio 0
	s_setprio 1
	v_mfma_f32_16x16x32_bf16 v[112:115], v[170:173], v[186:189], v[112:115]
	v_mfma_f32_16x16x32_bf16 v[108:111], v[178:181], v[186:189], v[108:111]
	v_mfma_f32_16x16x32_bf16 v[96:99], v[170:173], v[194:197], v[96:99]
	v_mfma_f32_16x16x32_bf16 v[92:95], v[178:181], v[194:197], v[92:95]
	v_mfma_f32_16x16x32_bf16 v[80:83], v[170:173], v[202:205], v[80:83]
	v_mfma_f32_16x16x32_bf16 v[76:79], v[178:181], v[202:205], v[76:79]
	v_mfma_f32_16x16x32_bf16 v[72:75], v[170:173], v[210:213], v[72:75]
	v_mfma_f32_16x16x32_bf16 v[68:71], v[178:181], v[210:213], v[68:71]
	v_mfma_f32_16x16x32_bf16 v[112:115], v[174:177], v[190:193], v[112:115]
	v_mfma_f32_16x16x32_bf16 v[108:111], v[182:185], v[190:193], v[108:111]
	v_mfma_f32_16x16x32_bf16 v[96:99], v[174:177], v[198:201], v[96:99]
	v_mfma_f32_16x16x32_bf16 v[92:95], v[182:185], v[198:201], v[92:95]
	v_mfma_f32_16x16x32_bf16 v[80:83], v[174:177], v[206:209], v[80:83]
	v_mfma_f32_16x16x32_bf16 v[76:79], v[182:185], v[206:209], v[76:79]
	v_mfma_f32_16x16x32_bf16 v[72:75], v[174:177], v[214:217], v[72:75]
	v_mfma_f32_16x16x32_bf16 v[68:71], v[182:185], v[214:217], v[68:71]
	s_setprio 0
	s_barrier
	s_add_i32 s0, s0, s46
	s_add_i32 m0, s0, 0xffffff80
	ds_read_b128 v[186:189], v152 offset:49152
	ds_read_b128 v[190:193], v152 offset:50176
	ds_read_b128 v[194:197], v152 offset:51200
	ds_read_b128 v[198:201], v152 offset:52224
	ds_read_b128 v[202:205], v152 offset:53248
	ds_read_b128 v[206:209], v152 offset:54272
	ds_read_b128 v[210:213], v152 offset:55296
	ds_read_b128 v[214:217], v152 offset:56320
	global_load_lds_dwordx4 v136, s[50:51] offset:128
	s_add_i32 m0, s0, 0x1f80
	s_add_i32 s0, s71, s46
	global_load_lds_dwordx4 v132, s[50:51] offset:128
	s_add_u32 s50, s50, 0x100080
	s_addc_u32 s51, s51, 0
	s_mov_b32 m0, s0
	s_nop 0
	global_load_lds_dwordx4 v136, s[50:51]
	s_add_i32 m0, s0, 0x2000
	s_nop 0
	global_load_lds_dwordx4 v132, s[50:51]
	s_add_i32 m0, s58, 0xffffff80
	s_nop 0
	global_load_lds_dwordx4 v138, s[52:53] offset:128
	s_add_i32 m0, s59, 0xffffff80
	s_nop 0
	global_load_lds_dwordx4 v134, s[52:53] offset:128
	s_waitcnt vmcnt(8)
	s_waitcnt lgkmcnt(0)
	s_barrier
	s_setprio 1
	s_waitcnt lgkmcnt(0)
	v_mfma_f32_16x16x32_bf16 v[64:67], v[154:157], v[186:189], v[64:67]
	v_mfma_f32_16x16x32_bf16 v[60:63], v[162:165], v[186:189], v[60:63]
	v_mfma_f32_16x16x32_bf16 v[56:59], v[154:157], v[194:197], v[56:59]
	v_mfma_f32_16x16x32_bf16 v[52:55], v[162:165], v[194:197], v[52:55]
	v_mfma_f32_16x16x32_bf16 v[40:43], v[154:157], v[202:205], v[40:43]
	v_mfma_f32_16x16x32_bf16 v[36:39], v[162:165], v[202:205], v[36:39]
	v_mfma_f32_16x16x32_bf16 v[24:27], v[154:157], v[210:213], v[24:27]
	v_mfma_f32_16x16x32_bf16 v[20:23], v[162:165], v[210:213], v[20:23]
	v_mfma_f32_16x16x32_bf16 v[64:67], v[158:161], v[190:193], v[64:67]
	v_mfma_f32_16x16x32_bf16 v[60:63], v[166:169], v[190:193], v[60:63]
	v_mfma_f32_16x16x32_bf16 v[56:59], v[158:161], v[198:201], v[56:59]
	v_mfma_f32_16x16x32_bf16 v[52:55], v[166:169], v[198:201], v[52:55]
	v_mfma_f32_16x16x32_bf16 v[40:43], v[158:161], v[206:209], v[40:43]
	v_mfma_f32_16x16x32_bf16 v[36:39], v[166:169], v[206:209], v[36:39]
	v_mfma_f32_16x16x32_bf16 v[24:27], v[158:161], v[214:217], v[24:27]
	v_mfma_f32_16x16x32_bf16 v[20:23], v[166:169], v[214:217], v[20:23]
	s_setprio 0
	s_setprio 1
	v_mfma_f32_16x16x32_bf16 v[48:51], v[170:173], v[186:189], v[48:51]
	v_mfma_f32_16x16x32_bf16 v[44:47], v[178:181], v[186:189], v[44:47]
	v_mfma_f32_16x16x32_bf16 v[32:35], v[170:173], v[194:197], v[32:35]
	v_mfma_f32_16x16x32_bf16 v[28:31], v[178:181], v[194:197], v[28:31]
	v_mfma_f32_16x16x32_bf16 v[16:19], v[170:173], v[202:205], v[16:19]
	v_mfma_f32_16x16x32_bf16 v[12:15], v[178:181], v[202:205], v[12:15]
	v_mfma_f32_16x16x32_bf16 v[8:11], v[170:173], v[210:213], v[8:11]
	v_mfma_f32_16x16x32_bf16 v[4:7], v[178:181], v[210:213], v[4:7]
	v_mfma_f32_16x16x32_bf16 v[48:51], v[174:177], v[190:193], v[48:51]
	v_mfma_f32_16x16x32_bf16 v[44:47], v[182:185], v[190:193], v[44:47]
	v_mfma_f32_16x16x32_bf16 v[32:35], v[174:177], v[198:201], v[32:35]
	v_mfma_f32_16x16x32_bf16 v[28:31], v[182:185], v[198:201], v[28:31]
	v_mfma_f32_16x16x32_bf16 v[16:19], v[174:177], v[206:209], v[16:19]
	v_mfma_f32_16x16x32_bf16 v[12:15], v[182:185], v[206:209], v[12:15]
	v_mfma_f32_16x16x32_bf16 v[8:11], v[174:177], v[214:217], v[8:11]
	v_mfma_f32_16x16x32_bf16 v[4:7], v[182:185], v[214:217], v[4:7]
	s_setprio 0
	s_barrier
	s_add_i32 s70, s70, 2
	s_add_u32 s42, s42, 0x100
	s_addc_u32 s43, s43, 0
	s_add_u32 s31, s31, 0x100
	s_addc_u32 s41, s41, 0
	s_cmp_gt_u32 s70, 13
	s_cbranch_scc0 .LBB0_1288
	s_and_b64 vcc, exec, s[14:15]
	s_cbranch_vccz .LBB0_1291
	s_barrier

.LBB0_1415:
	ds_read_b128 v[132:135], v187
	ds_read_b128 v[136:139], v187 offset:1024
	ds_read_b128 v[140:143], v187 offset:2048
	ds_read_b128 v[144:147], v187 offset:3072
	ds_read_b128 v[148:151], v188
	ds_read_b128 v[152:155], v188 offset:1024
	ds_read_b128 v[172:175], v188 offset:2048
	ds_read_b128 v[176:179], v188 offset:3072
	s_add_u32 s0, s42, 0xfffe0080
	s_addc_u32 s50, s43, -1
	s_cmp_eq_u32 s64, 4
	s_cselect_b32 s53, s25, s50
	s_cselect_b32 s52, s31, s0
	s_cselect_b32 s51, s23, s63
	s_cselect_b32 s50, s61, s62
	s_add_i32 m0, s41, 0xc000
	ds_read_b128 v[180:183], v189
	ds_read_b128 v[192:195], v189 offset:1024
	ds_read_b128 v[196:199], v189 offset:2048
	ds_read_b128 v[200:203], v189 offset:3072
	ds_read_b128 v[204:207], v189 offset:4096
	ds_read_b128 v[208:211], v189 offset:5120
	ds_read_b128 v[212:215], v189 offset:6144
	ds_read_b128 v[216:219], v189 offset:7168
	global_load_lds_dwordx4 v164, s[42:43]
	s_add_i32 m0, s41, 0xe000
	s_nop 0
	global_load_lds_dwordx4 v166, s[42:43]
	s_waitcnt vmcnt(8)
	s_waitcnt lgkmcnt(0)
	s_barrier
	s_setprio 1
	s_waitcnt lgkmcnt(0)
	v_mfma_f32_16x16x32_bf16 v[128:131], v[132:135], v[180:183], v[128:131]
	v_mfma_f32_16x16x32_bf16 v[124:127], v[140:143], v[180:183], v[124:127]
	v_mfma_f32_16x16x32_bf16 v[112:115], v[132:135], v[196:199], v[112:115]
	v_mfma_f32_16x16x32_bf16 v[108:111], v[140:143], v[196:199], v[108:111]
	v_mfma_f32_16x16x32_bf16 v[96:99], v[132:135], v[204:207], v[96:99]
	v_mfma_f32_16x16x32_bf16 v[92:95], v[140:143], v[204:207], v[92:95]
	v_mfma_f32_16x16x32_bf16 v[80:83], v[132:135], v[212:215], v[80:83]
	v_mfma_f32_16x16x32_bf16 v[76:79], v[140:143], v[212:215], v[76:79]
	v_mfma_f32_16x16x32_bf16 v[128:131], v[136:139], v[192:195], v[128:131]
	v_mfma_f32_16x16x32_bf16 v[124:127], v[144:147], v[192:195], v[124:127]
	v_mfma_f32_16x16x32_bf16 v[112:115], v[136:139], v[200:203], v[112:115]
	v_mfma_f32_16x16x32_bf16 v[108:111], v[144:147], v[200:203], v[108:111]
	v_mfma_f32_16x16x32_bf16 v[96:99], v[136:139], v[208:211], v[96:99]
	v_mfma_f32_16x16x32_bf16 v[92:95], v[144:147], v[208:211], v[92:95]
	v_mfma_f32_16x16x32_bf16 v[80:83], v[136:139], v[216:219], v[80:83]
	v_mfma_f32_16x16x32_bf16 v[76:79], v[144:147], v[216:219], v[76:79]
	s_setprio 0
	s_setprio 1
	v_mfma_f32_16x16x32_bf16 v[120:123], v[148:151], v[180:183], v[120:123]
	v_mfma_f32_16x16x32_bf16 v[116:119], v[172:175], v[180:183], v[116:119]
	v_mfma_f32_16x16x32_bf16 v[104:107], v[148:151], v[196:199], v[104:107]
	v_mfma_f32_16x16x32_bf16 v[100:103], v[172:175], v[196:199], v[100:103]
	v_mfma_f32_16x16x32_bf16 v[88:91], v[148:151], v[204:207], v[88:91]
	v_mfma_f32_16x16x32_bf16 v[84:87], v[172:175], v[204:207], v[84:87]
	v_mfma_f32_16x16x32_bf16 v[72:75], v[148:151], v[212:215], v[72:75]
	v_mfma_f32_16x16x32_bf16 v[68:71], v[172:175], v[212:215], v[68:71]
	v_mfma_f32_16x16x32_bf16 v[120:123], v[152:155], v[192:195], v[120:123]
	v_mfma_f32_16x16x32_bf16 v[116:119], v[176:179], v[192:195], v[116:119]
	v_mfma_f32_16x16x32_bf16 v[104:107], v[152:155], v[200:203], v[104:107]
	v_mfma_f32_16x16x32_bf16 v[100:103], v[176:179], v[200:203], v[100:103]
	v_mfma_f32_16x16x32_bf16 v[88:91], v[152:155], v[208:211], v[88:91]
	v_mfma_f32_16x16x32_bf16 v[84:87], v[176:179], v[208:211], v[84:87]
	v_mfma_f32_16x16x32_bf16 v[72:75], v[152:155], v[216:219], v[72:75]
	v_mfma_f32_16x16x32_bf16 v[68:71], v[176:179], v[216:219], v[68:71]
	s_setprio 0
	s_barrier
	s_add_i32 s0, s58, s45
	s_mov_b32 m0, s0
	ds_read_b128 v[180:183], v189 offset:16384
	ds_read_b128 v[192:195], v189 offset:17408
	ds_read_b128 v[196:199], v189 offset:18432
	ds_read_b128 v[200:203], v189 offset:19456
	ds_read_b128 v[204:207], v189 offset:20480
	ds_read_b128 v[208:211], v189 offset:21504
	ds_read_b128 v[212:215], v189 offset:22528
	ds_read_b128 v[216:219], v189 offset:23552
	global_load_lds_dwordx4 v158, s[50:51]
	s_add_i32 m0, s0, 0x2000
	s_add_u32 s66, s50, 0x20000
	s_addc_u32 s67, s51, 0
	s_add_i32 s0, s59, s45
	global_load_lds_dwordx4 v162, s[50:51]
	s_mov_b32 m0, s0
	s_nop 0
	global_load_lds_dwordx4 v158, s[66:67]
	s_add_i32 m0, s0, 0x2000
	s_nop 0
	global_load_lds_dwordx4 v162, s[66:67]
	s_mov_b32 m0, s41
	s_nop 0
	global_load_lds_dwordx4 v156, s[52:53]
	s_mov_b32 m0, s46
	s_nop 0
	global_load_lds_dwordx4 v160, s[52:53]
	s_waitcnt vmcnt(8)
	s_waitcnt lgkmcnt(0)
	s_barrier
	s_setprio 1
	s_waitcnt lgkmcnt(0)
	v_mfma_f32_16x16x32_bf16 v[64:67], v[132:135], v[180:183], v[64:67]
	v_mfma_f32_16x16x32_bf16 v[60:63], v[140:143], v[180:183], v[60:63]
	v_mfma_f32_16x16x32_bf16 v[48:51], v[132:135], v[196:199], v[48:51]
	v_mfma_f32_16x16x32_bf16 v[44:47], v[140:143], v[196:199], v[44:47]
	v_mfma_f32_16x16x32_bf16 v[32:35], v[132:135], v[204:207], v[32:35]
	v_mfma_f32_16x16x32_bf16 v[28:31], v[140:143], v[204:207], v[28:31]
	v_mfma_f32_16x16x32_bf16 v[16:19], v[132:135], v[212:215], v[16:19]
	v_mfma_f32_16x16x32_bf16 v[12:15], v[140:143], v[212:215], v[12:15]
	v_mfma_f32_16x16x32_bf16 v[64:67], v[136:139], v[192:195], v[64:67]
	v_mfma_f32_16x16x32_bf16 v[60:63], v[144:147], v[192:195], v[60:63]
	v_mfma_f32_16x16x32_bf16 v[48:51], v[136:139], v[200:203], v[48:51]
	v_mfma_f32_16x16x32_bf16 v[44:47], v[144:147], v[200:203], v[44:47]
	v_mfma_f32_16x16x32_bf16 v[32:35], v[136:139], v[208:211], v[32:35]
	v_mfma_f32_16x16x32_bf16 v[28:31], v[144:147], v[208:211], v[28:31]
	v_mfma_f32_16x16x32_bf16 v[16:19], v[136:139], v[216:219], v[16:19]
	v_mfma_f32_16x16x32_bf16 v[12:15], v[144:147], v[216:219], v[12:15]
	s_setprio 0
	s_setprio 1
	v_mfma_f32_16x16x32_bf16 v[56:59], v[148:151], v[180:183], v[56:59]
	v_mfma_f32_16x16x32_bf16 v[52:55], v[172:175], v[180:183], v[52:55]
	v_mfma_f32_16x16x32_bf16 v[40:43], v[148:151], v[196:199], v[40:43]
	v_mfma_f32_16x16x32_bf16 v[36:39], v[172:175], v[196:199], v[36:39]
	v_mfma_f32_16x16x32_bf16 v[24:27], v[148:151], v[204:207], v[24:27]
	v_mfma_f32_16x16x32_bf16 v[20:23], v[172:175], v[204:207], v[20:23]
	v_mfma_f32_16x16x32_bf16 v[8:11], v[148:151], v[212:215], v[8:11]
	v_mfma_f32_16x16x32_bf16 v[4:7], v[172:175], v[212:215], v[4:7]
	v_mfma_f32_16x16x32_bf16 v[56:59], v[152:155], v[192:195], v[56:59]
	v_mfma_f32_16x16x32_bf16 v[52:55], v[176:179], v[192:195], v[52:55]
	v_mfma_f32_16x16x32_bf16 v[40:43], v[152:155], v[200:203], v[40:43]
	v_mfma_f32_16x16x32_bf16 v[36:39], v[176:179], v[200:203], v[36:39]
	v_mfma_f32_16x16x32_bf16 v[24:27], v[152:155], v[208:211], v[24:27]
	v_mfma_f32_16x16x32_bf16 v[20:23], v[176:179], v[208:211], v[20:23]
	v_mfma_f32_16x16x32_bf16 v[8:11], v[152:155], v[216:219], v[8:11]
	v_mfma_f32_16x16x32_bf16 v[4:7], v[176:179], v[216:219], v[4:7]
	s_setprio 0
	s_barrier
	s_add_i32 s0, 0, 0x18000
	s_add_i32 s65, 0, 0x1c000
	v_add_u32_e32 v144, s0, v3
	v_add_u32_e32 v176, s65, v3
	ds_read_b128 v[132:135], v144
	ds_read_b128 v[136:139], v144 offset:1024
	ds_read_b128 v[140:143], v144 offset:2048
	ds_read_b128 v[144:147], v144 offset:3072
	ds_read_b128 v[148:151], v176
	ds_read_b128 v[152:155], v176 offset:1024
	ds_read_b128 v[172:175], v176 offset:2048
	ds_read_b128 v[176:179], v176 offset:3072
	s_add_u32 s98, s52, 0x20000
	s_addc_u32 s99, s53, 0
	s_mov_b32 m0, s47
	ds_read_b128 v[180:183], v189 offset:32768
	ds_read_b128 v[192:195], v189 offset:33792
	ds_read_b128 v[196:199], v189 offset:34816
	ds_read_b128 v[200:203], v189 offset:35840
	ds_read_b128 v[204:207], v189 offset:36864
	ds_read_b128 v[208:211], v189 offset:37888
	ds_read_b128 v[212:215], v189 offset:38912
	ds_read_b128 v[216:219], v189 offset:39936
	global_load_lds_dwordx4 v156, s[98:99]
	s_mov_b32 m0, s48
	s_nop 0
	global_load_lds_dwordx4 v160, s[98:99]
	s_waitcnt vmcnt(8)
	s_waitcnt lgkmcnt(0)
	s_barrier
	s_setprio 1
	s_waitcnt lgkmcnt(0)
	v_mfma_f32_16x16x32_bf16 v[128:131], v[132:135], v[180:183], v[128:131]
	v_mfma_f32_16x16x32_bf16 v[124:127], v[140:143], v[180:183], v[124:127]
	v_mfma_f32_16x16x32_bf16 v[112:115], v[132:135], v[196:199], v[112:115]
	v_mfma_f32_16x16x32_bf16 v[108:111], v[140:143], v[196:199], v[108:111]
	v_mfma_f32_16x16x32_bf16 v[96:99], v[132:135], v[204:207], v[96:99]
	v_mfma_f32_16x16x32_bf16 v[92:95], v[140:143], v[204:207], v[92:95]
	v_mfma_f32_16x16x32_bf16 v[80:83], v[132:135], v[212:215], v[80:83]
	v_mfma_f32_16x16x32_bf16 v[76:79], v[140:143], v[212:215], v[76:79]
	v_mfma_f32_16x16x32_bf16 v[128:131], v[136:139], v[192:195], v[128:131]
	v_mfma_f32_16x16x32_bf16 v[124:127], v[144:147], v[192:195], v[124:127]
	v_mfma_f32_16x16x32_bf16 v[112:115], v[136:139], v[200:203], v[112:115]
	v_mfma_f32_16x16x32_bf16 v[108:111], v[144:147], v[200:203], v[108:111]
	v_mfma_f32_16x16x32_bf16 v[96:99], v[136:139], v[208:211], v[96:99]
	v_mfma_f32_16x16x32_bf16 v[92:95], v[144:147], v[208:211], v[92:95]
	v_mfma_f32_16x16x32_bf16 v[80:83], v[136:139], v[216:219], v[80:83]
	v_mfma_f32_16x16x32_bf16 v[76:79], v[144:147], v[216:219], v[76:79]
	s_setprio 0
	s_setprio 1
	v_mfma_f32_16x16x32_bf16 v[120:123], v[148:151], v[180:183], v[120:123]
	v_mfma_f32_16x16x32_bf16 v[116:119], v[172:175], v[180:183], v[116:119]
	v_mfma_f32_16x16x32_bf16 v[104:107], v[148:151], v[196:199], v[104:107]
	v_mfma_f32_16x16x32_bf16 v[100:103], v[172:175], v[196:199], v[100:103]
	v_mfma_f32_16x16x32_bf16 v[88:91], v[148:151], v[204:207], v[88:91]
	v_mfma_f32_16x16x32_bf16 v[84:87], v[172:175], v[204:207], v[84:87]
	v_mfma_f32_16x16x32_bf16 v[72:75], v[148:151], v[212:215], v[72:75]
	v_mfma_f32_16x16x32_bf16 v[68:71], v[172:175], v[212:215], v[68:71]
	v_mfma_f32_16x16x32_bf16 v[120:123], v[152:155], v[192:195], v[120:123]
	v_mfma_f32_16x16x32_bf16 v[116:119], v[176:179], v[192:195], v[116:119]
	v_mfma_f32_16x16x32_bf16 v[104:107], v[152:155], v[200:203], v[104:107]
	v_mfma_f32_16x16x32_bf16 v[100:103], v[176:179], v[200:203], v[100:103]
	v_mfma_f32_16x16x32_bf16 v[88:91], v[152:155], v[208:211], v[88:91]
	v_mfma_f32_16x16x32_bf16 v[84:87], v[176:179], v[208:211], v[84:87]
	v_mfma_f32_16x16x32_bf16 v[72:75], v[152:155], v[216:219], v[72:75]
	v_mfma_f32_16x16x32_bf16 v[68:71], v[176:179], v[216:219], v[68:71]
	s_setprio 0
	s_barrier
	s_add_i32 s0, s0, s45
	s_add_i32 m0, s0, 0xffffff80
	ds_read_b128 v[180:183], v189 offset:49152
	ds_read_b128 v[192:195], v189 offset:50176
	ds_read_b128 v[196:199], v189 offset:51200
	ds_read_b128 v[200:203], v189 offset:52224
	ds_read_b128 v[204:207], v189 offset:53248
	ds_read_b128 v[208:211], v189 offset:54272
	ds_read_b128 v[212:215], v189 offset:55296
	ds_read_b128 v[216:219], v189 offset:56320
	global_load_lds_dwordx4 v158, s[50:51] offset:128
	s_add_i32 m0, s0, 0x1f80
	s_add_i32 s0, s65, s45
	global_load_lds_dwordx4 v162, s[50:51] offset:128
	s_add_u32 s50, s50, 0x20080
	s_addc_u32 s51, s51, 0
	s_mov_b32 m0, s0
	s_nop 0
	global_load_lds_dwordx4 v158, s[50:51]
	s_add_i32 m0, s0, 0x2000
	s_nop 0
	global_load_lds_dwordx4 v162, s[50:51]
	s_add_i32 m0, s56, 0xffffff80
	s_nop 0
	global_load_lds_dwordx4 v156, s[52:53] offset:128
	s_add_i32 m0, s57, 0xffffff80
	s_nop 0
	global_load_lds_dwordx4 v160, s[52:53] offset:128
	s_waitcnt vmcnt(8)
	s_waitcnt lgkmcnt(0)
	s_barrier
	s_setprio 1
	s_waitcnt lgkmcnt(0)
	v_mfma_f32_16x16x32_bf16 v[64:67], v[132:135], v[180:183], v[64:67]
	v_mfma_f32_16x16x32_bf16 v[60:63], v[140:143], v[180:183], v[60:63]
	v_mfma_f32_16x16x32_bf16 v[48:51], v[132:135], v[196:199], v[48:51]
	v_mfma_f32_16x16x32_bf16 v[44:47], v[140:143], v[196:199], v[44:47]
	v_mfma_f32_16x16x32_bf16 v[32:35], v[132:135], v[204:207], v[32:35]
	v_mfma_f32_16x16x32_bf16 v[28:31], v[140:143], v[204:207], v[28:31]
	v_mfma_f32_16x16x32_bf16 v[16:19], v[132:135], v[212:215], v[16:19]
	v_mfma_f32_16x16x32_bf16 v[12:15], v[140:143], v[212:215], v[12:15]
	v_mfma_f32_16x16x32_bf16 v[64:67], v[136:139], v[192:195], v[64:67]
	v_mfma_f32_16x16x32_bf16 v[60:63], v[144:147], v[192:195], v[60:63]
	v_mfma_f32_16x16x32_bf16 v[48:51], v[136:139], v[200:203], v[48:51]
	v_mfma_f32_16x16x32_bf16 v[44:47], v[144:147], v[200:203], v[44:47]
	v_mfma_f32_16x16x32_bf16 v[32:35], v[136:139], v[208:211], v[32:35]
	v_mfma_f32_16x16x32_bf16 v[28:31], v[144:147], v[208:211], v[28:31]
	v_mfma_f32_16x16x32_bf16 v[16:19], v[136:139], v[216:219], v[16:19]
	v_mfma_f32_16x16x32_bf16 v[12:15], v[144:147], v[216:219], v[12:15]
	s_setprio 0
	s_setprio 1
	v_mfma_f32_16x16x32_bf16 v[56:59], v[148:151], v[180:183], v[56:59]
	v_mfma_f32_16x16x32_bf16 v[52:55], v[172:175], v[180:183], v[52:55]
	v_mfma_f32_16x16x32_bf16 v[40:43], v[148:151], v[196:199], v[40:43]
	v_mfma_f32_16x16x32_bf16 v[36:39], v[172:175], v[196:199], v[36:39]
	v_mfma_f32_16x16x32_bf16 v[24:27], v[148:151], v[204:207], v[24:27]
	v_mfma_f32_16x16x32_bf16 v[20:23], v[172:175], v[204:207], v[20:23]
	v_mfma_f32_16x16x32_bf16 v[8:11], v[148:151], v[212:215], v[8:11]
	v_mfma_f32_16x16x32_bf16 v[4:7], v[172:175], v[212:215], v[4:7]
	v_mfma_f32_16x16x32_bf16 v[56:59], v[152:155], v[192:195], v[56:59]
	v_mfma_f32_16x16x32_bf16 v[52:55], v[176:179], v[192:195], v[52:55]
	v_mfma_f32_16x16x32_bf16 v[40:43], v[152:155], v[200:203], v[40:43]
	v_mfma_f32_16x16x32_bf16 v[36:39], v[176:179], v[200:203], v[36:39]
	v_mfma_f32_16x16x32_bf16 v[24:27], v[152:155], v[208:211], v[24:27]
	v_mfma_f32_16x16x32_bf16 v[20:23], v[176:179], v[208:211], v[20:23]
	v_mfma_f32_16x16x32_bf16 v[8:11], v[152:155], v[216:219], v[8:11]
	v_mfma_f32_16x16x32_bf16 v[4:7], v[176:179], v[216:219], v[4:7]
	s_setprio 0
	s_barrier
	s_add_i32 s64, s64, 2
	s_add_u32 s42, s42, 0x100
	s_addc_u32 s43, s43, 0
	s_add_u32 s62, s62, 0x100
	s_addc_u32 s63, s63, 0
	s_cmp_gt_u32 s64, 5
	s_cbranch_scc0 .LBB0_1415
	s_and_b64 vcc, exec, s[16:17]
	s_cbranch_vccz .LBB0_1418
	s_barrier

.LBB0_1503:
	ds_read_b128 v[132:135], v159
	ds_read_b128 v[164:167], v159 offset:1024
	ds_read_b128 v[168:171], v159 offset:2048
	ds_read_b128 v[172:175], v159 offset:3072
	ds_read_b128 v[176:179], v160
	ds_read_b128 v[180:183], v160 offset:1024
	ds_read_b128 v[184:187], v160 offset:2048
	ds_read_b128 v[188:191], v160 offset:3072
	s_add_u32 s0, s54, 0xfff00080
	s_addc_u32 s56, s55, -1
	s_cmp_eq_u32 s75, 60
	s_cselect_b32 s59, s31, s56
	s_cselect_b32 s58, s71, s0
	s_cselect_b32 s57, s29, s74
	s_cselect_b32 s56, s72, s73
	s_add_i32 m0, s48, 0xc000
	ds_read_b128 v[192:195], v161
	ds_read_b128 v[196:199], v161 offset:1024
	ds_read_b128 v[200:203], v161 offset:2048
	ds_read_b128 v[204:207], v161 offset:3072
	ds_read_b128 v[208:211], v161 offset:4096
	ds_read_b128 v[212:215], v161 offset:5120
	ds_read_b128 v[216:219], v161 offset:6144
	ds_read_b128 v[220:223], v161 offset:7168
	global_load_lds_dwordx4 v148, s[54:55]
	s_add_i32 m0, s48, 0xe000
	s_nop 0
	global_load_lds_dwordx4 v150, s[54:55]
	s_waitcnt vmcnt(8)
	s_waitcnt lgkmcnt(0)
	s_barrier
	s_setprio 1
	s_waitcnt lgkmcnt(0)
	v_mfma_f32_16x16x32_bf16 v[136:139], v[132:135], v[192:195], v[136:139]
	v_mfma_f32_16x16x32_bf16 v[128:131], v[168:171], v[192:195], v[128:131]
	v_mfma_f32_16x16x32_bf16 v[116:119], v[132:135], v[200:203], v[116:119]
	v_mfma_f32_16x16x32_bf16 v[112:115], v[168:171], v[200:203], v[112:115]
	v_mfma_f32_16x16x32_bf16 v[100:103], v[132:135], v[208:211], v[100:103]
	v_mfma_f32_16x16x32_bf16 v[96:99], v[168:171], v[208:211], v[96:99]
	v_mfma_f32_16x16x32_bf16 v[84:87], v[132:135], v[216:219], v[84:87]
	v_mfma_f32_16x16x32_bf16 v[80:83], v[168:171], v[216:219], v[80:83]
	v_mfma_f32_16x16x32_bf16 v[136:139], v[164:167], v[196:199], v[136:139]
	v_mfma_f32_16x16x32_bf16 v[128:131], v[172:175], v[196:199], v[128:131]
	v_mfma_f32_16x16x32_bf16 v[116:119], v[164:167], v[204:207], v[116:119]
	v_mfma_f32_16x16x32_bf16 v[112:115], v[172:175], v[204:207], v[112:115]
	v_mfma_f32_16x16x32_bf16 v[100:103], v[164:167], v[212:215], v[100:103]
	v_mfma_f32_16x16x32_bf16 v[96:99], v[172:175], v[212:215], v[96:99]
	v_mfma_f32_16x16x32_bf16 v[84:87], v[164:167], v[220:223], v[84:87]
	v_mfma_f32_16x16x32_bf16 v[80:83], v[172:175], v[220:223], v[80:83]
	s_setprio 0
	s_setprio 1
	v_mfma_f32_16x16x32_bf16 v[124:127], v[176:179], v[192:195], v[124:127]
	v_mfma_f32_16x16x32_bf16 v[120:123], v[184:187], v[192:195], v[120:123]
	v_mfma_f32_16x16x32_bf16 v[108:111], v[176:179], v[200:203], v[108:111]
	v_mfma_f32_16x16x32_bf16 v[104:107], v[184:187], v[200:203], v[104:107]
	v_mfma_f32_16x16x32_bf16 v[92:95], v[176:179], v[208:211], v[92:95]
	v_mfma_f32_16x16x32_bf16 v[88:91], v[184:187], v[208:211], v[88:91]
	v_mfma_f32_16x16x32_bf16 v[76:79], v[176:179], v[216:219], v[76:79]
	v_mfma_f32_16x16x32_bf16 v[72:75], v[184:187], v[216:219], v[72:75]
	v_mfma_f32_16x16x32_bf16 v[124:127], v[180:183], v[196:199], v[124:127]
	v_mfma_f32_16x16x32_bf16 v[120:123], v[188:191], v[196:199], v[120:123]
	v_mfma_f32_16x16x32_bf16 v[108:111], v[180:183], v[204:207], v[108:111]
	v_mfma_f32_16x16x32_bf16 v[104:107], v[188:191], v[204:207], v[104:107]
	v_mfma_f32_16x16x32_bf16 v[92:95], v[180:183], v[212:215], v[92:95]
	v_mfma_f32_16x16x32_bf16 v[88:91], v[188:191], v[212:215], v[88:91]
	v_mfma_f32_16x16x32_bf16 v[76:79], v[180:183], v[220:223], v[76:79]
	v_mfma_f32_16x16x32_bf16 v[72:75], v[188:191], v[220:223], v[72:75]
	s_setprio 0
	s_barrier
	s_add_i32 s0, s65, s47
	s_mov_b32 m0, s0
	ds_read_b128 v[192:195], v161 offset:16384
	ds_read_b128 v[196:199], v161 offset:17408
	ds_read_b128 v[200:203], v161 offset:18432
	ds_read_b128 v[204:207], v161 offset:19456
	ds_read_b128 v[208:211], v161 offset:20480
	ds_read_b128 v[212:215], v161 offset:21504
	ds_read_b128 v[216:219], v161 offset:22528
	ds_read_b128 v[220:223], v161 offset:23552
	global_load_lds_dwordx4 v142, s[56:57]
	s_add_i32 m0, s0, 0x2000
	s_add_u32 s76, s56, 0x100000
	s_addc_u32 s77, s57, 0
	s_add_i32 s0, s66, s47
	global_load_lds_dwordx4 v146, s[56:57]
	s_mov_b32 m0, s0
	s_nop 0
	global_load_lds_dwordx4 v142, s[76:77]
	s_add_i32 m0, s0, 0x2000
	s_nop 0
	global_load_lds_dwordx4 v146, s[76:77]
	s_mov_b32 m0, s48
	s_nop 0
	global_load_lds_dwordx4 v140, s[58:59]
	s_mov_b32 m0, s49
	s_nop 0
	global_load_lds_dwordx4 v144, s[58:59]
	s_waitcnt vmcnt(8)
	s_waitcnt lgkmcnt(0)
	s_barrier
	s_setprio 1
	s_waitcnt lgkmcnt(0)
	v_mfma_f32_16x16x32_bf16 v[68:71], v[132:135], v[192:195], v[68:71]
	v_mfma_f32_16x16x32_bf16 v[64:67], v[168:171], v[192:195], v[64:67]
	v_mfma_f32_16x16x32_bf16 v[52:55], v[132:135], v[200:203], v[52:55]
	v_mfma_f32_16x16x32_bf16 v[48:51], v[168:171], v[200:203], v[48:51]
	v_mfma_f32_16x16x32_bf16 v[36:39], v[132:135], v[208:211], v[36:39]
	v_mfma_f32_16x16x32_bf16 v[32:35], v[168:171], v[208:211], v[32:35]
	v_mfma_f32_16x16x32_bf16 v[20:23], v[132:135], v[216:219], v[20:23]
	v_mfma_f32_16x16x32_bf16 v[16:19], v[168:171], v[216:219], v[16:19]
	v_mfma_f32_16x16x32_bf16 v[68:71], v[164:167], v[196:199], v[68:71]
	v_mfma_f32_16x16x32_bf16 v[64:67], v[172:175], v[196:199], v[64:67]
	v_mfma_f32_16x16x32_bf16 v[52:55], v[164:167], v[204:207], v[52:55]
	v_mfma_f32_16x16x32_bf16 v[48:51], v[172:175], v[204:207], v[48:51]
	v_mfma_f32_16x16x32_bf16 v[36:39], v[164:167], v[212:215], v[36:39]
	v_mfma_f32_16x16x32_bf16 v[32:35], v[172:175], v[212:215], v[32:35]
	v_mfma_f32_16x16x32_bf16 v[20:23], v[164:167], v[220:223], v[20:23]
	v_mfma_f32_16x16x32_bf16 v[16:19], v[172:175], v[220:223], v[16:19]
	s_setprio 0
	s_setprio 1
	v_mfma_f32_16x16x32_bf16 v[60:63], v[176:179], v[192:195], v[60:63]
	v_mfma_f32_16x16x32_bf16 v[56:59], v[184:187], v[192:195], v[56:59]
	v_mfma_f32_16x16x32_bf16 v[44:47], v[176:179], v[200:203], v[44:47]
	v_mfma_f32_16x16x32_bf16 v[40:43], v[184:187], v[200:203], v[40:43]
	v_mfma_f32_16x16x32_bf16 v[28:31], v[176:179], v[208:211], v[28:31]
	v_mfma_f32_16x16x32_bf16 v[24:27], v[184:187], v[208:211], v[24:27]
	v_mfma_f32_16x16x32_bf16 v[12:15], v[176:179], v[216:219], v[12:15]
	v_mfma_f32_16x16x32_bf16 v[8:11], v[184:187], v[216:219], v[8:11]
	v_mfma_f32_16x16x32_bf16 v[60:63], v[180:183], v[196:199], v[60:63]
	v_mfma_f32_16x16x32_bf16 v[56:59], v[188:191], v[196:199], v[56:59]
	v_mfma_f32_16x16x32_bf16 v[44:47], v[180:183], v[204:207], v[44:47]
	v_mfma_f32_16x16x32_bf16 v[40:43], v[188:191], v[204:207], v[40:43]
	v_mfma_f32_16x16x32_bf16 v[28:31], v[180:183], v[212:215], v[28:31]
	v_mfma_f32_16x16x32_bf16 v[24:27], v[188:191], v[212:215], v[24:27]
	v_mfma_f32_16x16x32_bf16 v[12:15], v[180:183], v[220:223], v[12:15]
	v_mfma_f32_16x16x32_bf16 v[8:11], v[188:191], v[220:223], v[8:11]
	s_setprio 0
	s_barrier
	s_add_i32 s0, 0, 0x18000
	s_add_i32 s76, 0, 0x1c000
	v_add_u32_e32 v172, s0, v156
	v_add_u32_e32 v188, s76, v156
	ds_read_b128 v[132:135], v172
	ds_read_b128 v[164:167], v172 offset:1024
	ds_read_b128 v[168:171], v172 offset:2048
	ds_read_b128 v[172:175], v172 offset:3072
	ds_read_b128 v[176:179], v188
	ds_read_b128 v[180:183], v188 offset:1024
	ds_read_b128 v[184:187], v188 offset:2048
	ds_read_b128 v[188:191], v188 offset:3072
	s_add_u32 s98, s58, 0x100000
	s_addc_u32 s99, s59, 0
	s_mov_b32 m0, s51
	ds_read_b128 v[192:195], v161 offset:32768
	ds_read_b128 v[196:199], v161 offset:33792
	ds_read_b128 v[200:203], v161 offset:34816
	ds_read_b128 v[204:207], v161 offset:35840
	ds_read_b128 v[208:211], v161 offset:36864
	ds_read_b128 v[212:215], v161 offset:37888
	ds_read_b128 v[216:219], v161 offset:38912
	ds_read_b128 v[220:223], v161 offset:39936
	global_load_lds_dwordx4 v140, s[98:99]
	s_mov_b32 m0, s53
	s_nop 0
	global_load_lds_dwordx4 v144, s[98:99]
	s_waitcnt vmcnt(8)
	s_waitcnt lgkmcnt(0)
	s_barrier
	s_setprio 1
	s_waitcnt lgkmcnt(0)
	v_mfma_f32_16x16x32_bf16 v[136:139], v[132:135], v[192:195], v[136:139]
	v_mfma_f32_16x16x32_bf16 v[128:131], v[168:171], v[192:195], v[128:131]
	v_mfma_f32_16x16x32_bf16 v[116:119], v[132:135], v[200:203], v[116:119]
	v_mfma_f32_16x16x32_bf16 v[112:115], v[168:171], v[200:203], v[112:115]
	v_mfma_f32_16x16x32_bf16 v[100:103], v[132:135], v[208:211], v[100:103]
	v_mfma_f32_16x16x32_bf16 v[96:99], v[168:171], v[208:211], v[96:99]
	v_mfma_f32_16x16x32_bf16 v[84:87], v[132:135], v[216:219], v[84:87]
	v_mfma_f32_16x16x32_bf16 v[80:83], v[168:171], v[216:219], v[80:83]
	v_mfma_f32_16x16x32_bf16 v[136:139], v[164:167], v[196:199], v[136:139]
	v_mfma_f32_16x16x32_bf16 v[128:131], v[172:175], v[196:199], v[128:131]
	v_mfma_f32_16x16x32_bf16 v[116:119], v[164:167], v[204:207], v[116:119]
	v_mfma_f32_16x16x32_bf16 v[112:115], v[172:175], v[204:207], v[112:115]
	v_mfma_f32_16x16x32_bf16 v[100:103], v[164:167], v[212:215], v[100:103]
	v_mfma_f32_16x16x32_bf16 v[96:99], v[172:175], v[212:215], v[96:99]
	v_mfma_f32_16x16x32_bf16 v[84:87], v[164:167], v[220:223], v[84:87]
	v_mfma_f32_16x16x32_bf16 v[80:83], v[172:175], v[220:223], v[80:83]
	s_setprio 0
	s_setprio 1
	v_mfma_f32_16x16x32_bf16 v[124:127], v[176:179], v[192:195], v[124:127]
	v_mfma_f32_16x16x32_bf16 v[120:123], v[184:187], v[192:195], v[120:123]
	v_mfma_f32_16x16x32_bf16 v[108:111], v[176:179], v[200:203], v[108:111]
	v_mfma_f32_16x16x32_bf16 v[104:107], v[184:187], v[200:203], v[104:107]
	v_mfma_f32_16x16x32_bf16 v[92:95], v[176:179], v[208:211], v[92:95]
	v_mfma_f32_16x16x32_bf16 v[88:91], v[184:187], v[208:211], v[88:91]
	v_mfma_f32_16x16x32_bf16 v[76:79], v[176:179], v[216:219], v[76:79]
	v_mfma_f32_16x16x32_bf16 v[72:75], v[184:187], v[216:219], v[72:75]
	v_mfma_f32_16x16x32_bf16 v[124:127], v[180:183], v[196:199], v[124:127]
	v_mfma_f32_16x16x32_bf16 v[120:123], v[188:191], v[196:199], v[120:123]
	v_mfma_f32_16x16x32_bf16 v[108:111], v[180:183], v[204:207], v[108:111]
	v_mfma_f32_16x16x32_bf16 v[104:107], v[188:191], v[204:207], v[104:107]
	v_mfma_f32_16x16x32_bf16 v[92:95], v[180:183], v[212:215], v[92:95]
	v_mfma_f32_16x16x32_bf16 v[88:91], v[188:191], v[212:215], v[88:91]
	v_mfma_f32_16x16x32_bf16 v[76:79], v[180:183], v[220:223], v[76:79]
	v_mfma_f32_16x16x32_bf16 v[72:75], v[188:191], v[220:223], v[72:75]
	s_setprio 0
	s_barrier
	s_add_i32 s0, s0, s47
	s_add_i32 m0, s0, 0xffffff80
	ds_read_b128 v[192:195], v161 offset:49152
	ds_read_b128 v[196:199], v161 offset:50176
	ds_read_b128 v[200:203], v161 offset:51200
	ds_read_b128 v[204:207], v161 offset:52224
	ds_read_b128 v[208:211], v161 offset:53248
	ds_read_b128 v[212:215], v161 offset:54272
	ds_read_b128 v[216:219], v161 offset:55296
	ds_read_b128 v[220:223], v161 offset:56320
	global_load_lds_dwordx4 v142, s[56:57] offset:128
	s_add_i32 m0, s0, 0x1f80
	s_add_i32 s0, s76, s47
	global_load_lds_dwordx4 v146, s[56:57] offset:128
	s_add_u32 s56, s56, 0x100080
	s_addc_u32 s57, s57, 0
	s_mov_b32 m0, s0
	s_nop 0
	global_load_lds_dwordx4 v142, s[56:57]
	s_add_i32 m0, s0, 0x2000
	s_nop 0
	global_load_lds_dwordx4 v146, s[56:57]
	s_add_i32 m0, s62, 0xffffff80
	s_nop 0
	global_load_lds_dwordx4 v140, s[58:59] offset:128
	s_add_i32 m0, s63, 0xffffff80
	s_nop 0
	global_load_lds_dwordx4 v144, s[58:59] offset:128
	s_waitcnt vmcnt(8)
	s_waitcnt lgkmcnt(0)
	s_barrier
	s_setprio 1
	s_waitcnt lgkmcnt(0)
	v_mfma_f32_16x16x32_bf16 v[68:71], v[132:135], v[192:195], v[68:71]
	v_mfma_f32_16x16x32_bf16 v[64:67], v[168:171], v[192:195], v[64:67]
	v_mfma_f32_16x16x32_bf16 v[52:55], v[132:135], v[200:203], v[52:55]
	v_mfma_f32_16x16x32_bf16 v[48:51], v[168:171], v[200:203], v[48:51]
	v_mfma_f32_16x16x32_bf16 v[36:39], v[132:135], v[208:211], v[36:39]
	v_mfma_f32_16x16x32_bf16 v[32:35], v[168:171], v[208:211], v[32:35]
	v_mfma_f32_16x16x32_bf16 v[20:23], v[132:135], v[216:219], v[20:23]
	v_mfma_f32_16x16x32_bf16 v[16:19], v[168:171], v[216:219], v[16:19]
	v_mfma_f32_16x16x32_bf16 v[68:71], v[164:167], v[196:199], v[68:71]
	v_mfma_f32_16x16x32_bf16 v[64:67], v[172:175], v[196:199], v[64:67]
	v_mfma_f32_16x16x32_bf16 v[52:55], v[164:167], v[204:207], v[52:55]
	v_mfma_f32_16x16x32_bf16 v[48:51], v[172:175], v[204:207], v[48:51]
	v_mfma_f32_16x16x32_bf16 v[36:39], v[164:167], v[212:215], v[36:39]
	v_mfma_f32_16x16x32_bf16 v[32:35], v[172:175], v[212:215], v[32:35]
	v_mfma_f32_16x16x32_bf16 v[20:23], v[164:167], v[220:223], v[20:23]
	v_mfma_f32_16x16x32_bf16 v[16:19], v[172:175], v[220:223], v[16:19]
	s_setprio 0
	s_setprio 1
	v_mfma_f32_16x16x32_bf16 v[60:63], v[176:179], v[192:195], v[60:63]
	v_mfma_f32_16x16x32_bf16 v[56:59], v[184:187], v[192:195], v[56:59]
	v_mfma_f32_16x16x32_bf16 v[44:47], v[176:179], v[200:203], v[44:47]
	v_mfma_f32_16x16x32_bf16 v[40:43], v[184:187], v[200:203], v[40:43]
	v_mfma_f32_16x16x32_bf16 v[28:31], v[176:179], v[208:211], v[28:31]
	v_mfma_f32_16x16x32_bf16 v[24:27], v[184:187], v[208:211], v[24:27]
	v_mfma_f32_16x16x32_bf16 v[12:15], v[176:179], v[216:219], v[12:15]
	v_mfma_f32_16x16x32_bf16 v[8:11], v[184:187], v[216:219], v[8:11]
	v_mfma_f32_16x16x32_bf16 v[60:63], v[180:183], v[196:199], v[60:63]
	v_mfma_f32_16x16x32_bf16 v[56:59], v[188:191], v[196:199], v[56:59]
	v_mfma_f32_16x16x32_bf16 v[44:47], v[180:183], v[204:207], v[44:47]
	v_mfma_f32_16x16x32_bf16 v[40:43], v[188:191], v[204:207], v[40:43]
	v_mfma_f32_16x16x32_bf16 v[28:31], v[180:183], v[212:215], v[28:31]
	v_mfma_f32_16x16x32_bf16 v[24:27], v[188:191], v[212:215], v[24:27]
	v_mfma_f32_16x16x32_bf16 v[12:15], v[180:183], v[220:223], v[12:15]
	v_mfma_f32_16x16x32_bf16 v[8:11], v[188:191], v[220:223], v[8:11]
	s_setprio 0
	s_barrier
	s_add_i32 s75, s75, 2
	s_add_u32 s54, s54, 0x100
	s_addc_u32 s55, s55, 0
	s_add_u32 s73, s73, 0x100
	s_addc_u32 s74, s74, 0
	s_cmp_gt_u32 s75, 61
	s_cbranch_scc0 .LBB0_1503
	s_and_b64 vcc, exec, s[26:27]
	s_cbranch_vccz .LBB0_1506
	s_barrier

.LBB0_1672:
	ds_read_b128 v[132:135], v193
	ds_read_b128 v[136:139], v193 offset:1024
	ds_read_b128 v[140:143], v193 offset:2048
	ds_read_b128 v[144:147], v193 offset:3072
	ds_read_b128 v[148:151], v194
	ds_read_b128 v[152:155], v194 offset:1024
	ds_read_b128 v[172:175], v194 offset:2048
	ds_read_b128 v[176:179], v194 offset:3072
	s_add_u32 s0, s30, 0xffd50080
	s_addc_u32 s42, s31, -1
	s_cmpk_eq_i32 s66, 0xa8
	s_cselect_b32 s51, s7, s42
	s_cselect_b32 s50, s6, s0
	s_cselect_b32 s43, s29, s65
	s_cselect_b32 s42, s28, s64
	s_add_i32 m0, s46, 0xc000
	ds_read_b128 v[180:183], v195
	ds_read_b128 v[198:201], v195 offset:1024
	ds_read_b128 v[202:205], v195 offset:2048
	ds_read_b128 v[206:209], v195 offset:3072
	ds_read_b128 v[210:213], v195 offset:4096
	ds_read_b128 v[214:217], v195 offset:5120
	ds_read_b128 v[218:221], v195 offset:6144
	ds_read_b128 v[222:225], v195 offset:7168
	global_load_lds_dwordx4 v164, s[30:31]
	s_add_i32 m0, s46, 0xe000
	s_nop 0
	global_load_lds_dwordx4 v166, s[30:31]
	s_waitcnt vmcnt(8)
	s_waitcnt lgkmcnt(0)
	s_barrier
	s_setprio 1
	s_waitcnt lgkmcnt(0)
	v_mfma_f32_16x16x32_bf16 v[128:131], v[132:135], v[180:183], v[128:131]
	v_mfma_f32_16x16x32_bf16 v[124:127], v[140:143], v[180:183], v[124:127]
	v_mfma_f32_16x16x32_bf16 v[112:115], v[132:135], v[202:205], v[112:115]
	v_mfma_f32_16x16x32_bf16 v[108:111], v[140:143], v[202:205], v[108:111]
	v_mfma_f32_16x16x32_bf16 v[96:99], v[132:135], v[210:213], v[96:99]
	v_mfma_f32_16x16x32_bf16 v[92:95], v[140:143], v[210:213], v[92:95]
	v_mfma_f32_16x16x32_bf16 v[80:83], v[132:135], v[218:221], v[80:83]
	v_mfma_f32_16x16x32_bf16 v[76:79], v[140:143], v[218:221], v[76:79]
	v_mfma_f32_16x16x32_bf16 v[128:131], v[136:139], v[198:201], v[128:131]
	v_mfma_f32_16x16x32_bf16 v[124:127], v[144:147], v[198:201], v[124:127]
	v_mfma_f32_16x16x32_bf16 v[112:115], v[136:139], v[206:209], v[112:115]
	v_mfma_f32_16x16x32_bf16 v[108:111], v[144:147], v[206:209], v[108:111]
	v_mfma_f32_16x16x32_bf16 v[96:99], v[136:139], v[214:217], v[96:99]
	v_mfma_f32_16x16x32_bf16 v[92:95], v[144:147], v[214:217], v[92:95]
	v_mfma_f32_16x16x32_bf16 v[80:83], v[136:139], v[222:225], v[80:83]
	v_mfma_f32_16x16x32_bf16 v[76:79], v[144:147], v[222:225], v[76:79]
	s_setprio 0
	s_setprio 1
	v_mfma_f32_16x16x32_bf16 v[120:123], v[148:151], v[180:183], v[120:123]
	v_mfma_f32_16x16x32_bf16 v[116:119], v[172:175], v[180:183], v[116:119]
	v_mfma_f32_16x16x32_bf16 v[104:107], v[148:151], v[202:205], v[104:107]
	v_mfma_f32_16x16x32_bf16 v[100:103], v[172:175], v[202:205], v[100:103]
	v_mfma_f32_16x16x32_bf16 v[88:91], v[148:151], v[210:213], v[88:91]
	v_mfma_f32_16x16x32_bf16 v[84:87], v[172:175], v[210:213], v[84:87]
	v_mfma_f32_16x16x32_bf16 v[72:75], v[148:151], v[218:221], v[72:75]
	v_mfma_f32_16x16x32_bf16 v[68:71], v[172:175], v[218:221], v[68:71]
	v_mfma_f32_16x16x32_bf16 v[120:123], v[152:155], v[198:201], v[120:123]
	v_mfma_f32_16x16x32_bf16 v[116:119], v[176:179], v[198:201], v[116:119]
	v_mfma_f32_16x16x32_bf16 v[104:107], v[152:155], v[206:209], v[104:107]
	v_mfma_f32_16x16x32_bf16 v[100:103], v[176:179], v[206:209], v[100:103]
	v_mfma_f32_16x16x32_bf16 v[88:91], v[152:155], v[214:217], v[88:91]
	v_mfma_f32_16x16x32_bf16 v[84:87], v[176:179], v[214:217], v[84:87]
	v_mfma_f32_16x16x32_bf16 v[72:75], v[152:155], v[222:225], v[72:75]
	v_mfma_f32_16x16x32_bf16 v[68:71], v[176:179], v[222:225], v[68:71]
	s_setprio 0
	s_barrier
	s_add_i32 s0, s57, s45
	s_mov_b32 m0, s0
	ds_read_b128 v[180:183], v195 offset:16384
	ds_read_b128 v[198:201], v195 offset:17408
	ds_read_b128 v[202:205], v195 offset:18432
	ds_read_b128 v[206:209], v195 offset:19456
	ds_read_b128 v[210:213], v195 offset:20480
	ds_read_b128 v[214:217], v195 offset:21504
	ds_read_b128 v[218:221], v195 offset:22528
	ds_read_b128 v[222:225], v195 offset:23552
	global_load_lds_dwordx4 v158, s[42:43]
	s_add_i32 m0, s0, 0x2000
	s_add_u32 s70, s42, 0x2b0000
	s_addc_u32 s71, s43, 0
	s_add_i32 s0, s58, s45
	global_load_lds_dwordx4 v162, s[42:43]
	s_mov_b32 m0, s0
	s_nop 0
	global_load_lds_dwordx4 v158, s[70:71]
	s_add_i32 m0, s0, 0x2000
	s_nop 0
	global_load_lds_dwordx4 v162, s[70:71]
	s_mov_b32 m0, s46
	s_nop 0
	global_load_lds_dwordx4 v156, s[50:51]
	s_mov_b32 m0, s47
	s_nop 0
	global_load_lds_dwordx4 v160, s[50:51]
	s_waitcnt vmcnt(8)
	s_waitcnt lgkmcnt(0)
	s_barrier
	s_setprio 1
	s_waitcnt lgkmcnt(0)
	v_mfma_f32_16x16x32_bf16 v[64:67], v[132:135], v[180:183], v[64:67]
	v_mfma_f32_16x16x32_bf16 v[60:63], v[140:143], v[180:183], v[60:63]
	v_mfma_f32_16x16x32_bf16 v[48:51], v[132:135], v[202:205], v[48:51]
	v_mfma_f32_16x16x32_bf16 v[44:47], v[140:143], v[202:205], v[44:47]
	v_mfma_f32_16x16x32_bf16 v[32:35], v[132:135], v[210:213], v[32:35]
	v_mfma_f32_16x16x32_bf16 v[28:31], v[140:143], v[210:213], v[28:31]
	v_mfma_f32_16x16x32_bf16 v[16:19], v[132:135], v[218:221], v[16:19]
	v_mfma_f32_16x16x32_bf16 v[12:15], v[140:143], v[218:221], v[12:15]
	v_mfma_f32_16x16x32_bf16 v[64:67], v[136:139], v[198:201], v[64:67]
	v_mfma_f32_16x16x32_bf16 v[60:63], v[144:147], v[198:201], v[60:63]
	v_mfma_f32_16x16x32_bf16 v[48:51], v[136:139], v[206:209], v[48:51]
	v_mfma_f32_16x16x32_bf16 v[44:47], v[144:147], v[206:209], v[44:47]
	v_mfma_f32_16x16x32_bf16 v[32:35], v[136:139], v[214:217], v[32:35]
	v_mfma_f32_16x16x32_bf16 v[28:31], v[144:147], v[214:217], v[28:31]
	v_mfma_f32_16x16x32_bf16 v[16:19], v[136:139], v[222:225], v[16:19]
	v_mfma_f32_16x16x32_bf16 v[12:15], v[144:147], v[222:225], v[12:15]
	s_setprio 0
	s_setprio 1
	v_mfma_f32_16x16x32_bf16 v[56:59], v[148:151], v[180:183], v[56:59]
	v_mfma_f32_16x16x32_bf16 v[52:55], v[172:175], v[180:183], v[52:55]
	v_mfma_f32_16x16x32_bf16 v[40:43], v[148:151], v[202:205], v[40:43]
	v_mfma_f32_16x16x32_bf16 v[36:39], v[172:175], v[202:205], v[36:39]
	v_mfma_f32_16x16x32_bf16 v[24:27], v[148:151], v[210:213], v[24:27]
	v_mfma_f32_16x16x32_bf16 v[20:23], v[172:175], v[210:213], v[20:23]
	v_mfma_f32_16x16x32_bf16 v[8:11], v[148:151], v[218:221], v[8:11]
	v_mfma_f32_16x16x32_bf16 v[4:7], v[172:175], v[218:221], v[4:7]
	v_mfma_f32_16x16x32_bf16 v[56:59], v[152:155], v[198:201], v[56:59]
	v_mfma_f32_16x16x32_bf16 v[52:55], v[176:179], v[198:201], v[52:55]
	v_mfma_f32_16x16x32_bf16 v[40:43], v[152:155], v[206:209], v[40:43]
	v_mfma_f32_16x16x32_bf16 v[36:39], v[176:179], v[206:209], v[36:39]
	v_mfma_f32_16x16x32_bf16 v[24:27], v[152:155], v[214:217], v[24:27]
	v_mfma_f32_16x16x32_bf16 v[20:23], v[176:179], v[214:217], v[20:23]
	v_mfma_f32_16x16x32_bf16 v[8:11], v[152:155], v[222:225], v[8:11]
	v_mfma_f32_16x16x32_bf16 v[4:7], v[176:179], v[222:225], v[4:7]
	s_setprio 0
	s_barrier
	s_add_i32 s0, 0, 0x18000
	s_add_i32 s67, 0, 0x1c000
	v_add_u32_e32 v144, s0, v191
	v_add_u32_e32 v176, s67, v191
	ds_read_b128 v[132:135], v144
	ds_read_b128 v[136:139], v144 offset:1024
	ds_read_b128 v[140:143], v144 offset:2048
	ds_read_b128 v[144:147], v144 offset:3072
	ds_read_b128 v[148:151], v176
	ds_read_b128 v[152:155], v176 offset:1024
	ds_read_b128 v[172:175], v176 offset:2048
	ds_read_b128 v[176:179], v176 offset:3072
	s_add_u32 s98, s50, 0x2b0000
	s_addc_u32 s99, s51, 0
	s_mov_b32 m0, s48
	ds_read_b128 v[180:183], v195 offset:32768
	ds_read_b128 v[198:201], v195 offset:33792
	ds_read_b128 v[202:205], v195 offset:34816
	ds_read_b128 v[206:209], v195 offset:35840
	ds_read_b128 v[210:213], v195 offset:36864
	ds_read_b128 v[214:217], v195 offset:37888
	ds_read_b128 v[218:221], v195 offset:38912
	ds_read_b128 v[222:225], v195 offset:39936
	global_load_lds_dwordx4 v156, s[98:99]
	s_mov_b32 m0, s49
	s_nop 0
	global_load_lds_dwordx4 v160, s[98:99]
	s_waitcnt vmcnt(8)
	s_waitcnt lgkmcnt(0)
	s_barrier
	s_setprio 1
	s_waitcnt lgkmcnt(0)
	v_mfma_f32_16x16x32_bf16 v[128:131], v[132:135], v[180:183], v[128:131]
	v_mfma_f32_16x16x32_bf16 v[124:127], v[140:143], v[180:183], v[124:127]
	v_mfma_f32_16x16x32_bf16 v[112:115], v[132:135], v[202:205], v[112:115]
	v_mfma_f32_16x16x32_bf16 v[108:111], v[140:143], v[202:205], v[108:111]
	v_mfma_f32_16x16x32_bf16 v[96:99], v[132:135], v[210:213], v[96:99]
	v_mfma_f32_16x16x32_bf16 v[92:95], v[140:143], v[210:213], v[92:95]
	v_mfma_f32_16x16x32_bf16 v[80:83], v[132:135], v[218:221], v[80:83]
	v_mfma_f32_16x16x32_bf16 v[76:79], v[140:143], v[218:221], v[76:79]
	v_mfma_f32_16x16x32_bf16 v[128:131], v[136:139], v[198:201], v[128:131]
	v_mfma_f32_16x16x32_bf16 v[124:127], v[144:147], v[198:201], v[124:127]
	v_mfma_f32_16x16x32_bf16 v[112:115], v[136:139], v[206:209], v[112:115]
	v_mfma_f32_16x16x32_bf16 v[108:111], v[144:147], v[206:209], v[108:111]
	v_mfma_f32_16x16x32_bf16 v[96:99], v[136:139], v[214:217], v[96:99]
	v_mfma_f32_16x16x32_bf16 v[92:95], v[144:147], v[214:217], v[92:95]
	v_mfma_f32_16x16x32_bf16 v[80:83], v[136:139], v[222:225], v[80:83]
	v_mfma_f32_16x16x32_bf16 v[76:79], v[144:147], v[222:225], v[76:79]
	s_setprio 0
	s_setprio 1
	v_mfma_f32_16x16x32_bf16 v[120:123], v[148:151], v[180:183], v[120:123]
	v_mfma_f32_16x16x32_bf16 v[116:119], v[172:175], v[180:183], v[116:119]
	v_mfma_f32_16x16x32_bf16 v[104:107], v[148:151], v[202:205], v[104:107]
	v_mfma_f32_16x16x32_bf16 v[100:103], v[172:175], v[202:205], v[100:103]
	v_mfma_f32_16x16x32_bf16 v[88:91], v[148:151], v[210:213], v[88:91]
	v_mfma_f32_16x16x32_bf16 v[84:87], v[172:175], v[210:213], v[84:87]
	v_mfma_f32_16x16x32_bf16 v[72:75], v[148:151], v[218:221], v[72:75]
	v_mfma_f32_16x16x32_bf16 v[68:71], v[172:175], v[218:221], v[68:71]
	v_mfma_f32_16x16x32_bf16 v[120:123], v[152:155], v[198:201], v[120:123]
	v_mfma_f32_16x16x32_bf16 v[116:119], v[176:179], v[198:201], v[116:119]
	v_mfma_f32_16x16x32_bf16 v[104:107], v[152:155], v[206:209], v[104:107]
	v_mfma_f32_16x16x32_bf16 v[100:103], v[176:179], v[206:209], v[100:103]
	v_mfma_f32_16x16x32_bf16 v[88:91], v[152:155], v[214:217], v[88:91]
	v_mfma_f32_16x16x32_bf16 v[84:87], v[176:179], v[214:217], v[84:87]
	v_mfma_f32_16x16x32_bf16 v[72:75], v[152:155], v[222:225], v[72:75]
	v_mfma_f32_16x16x32_bf16 v[68:71], v[176:179], v[222:225], v[68:71]
	s_setprio 0
	s_barrier
	s_add_i32 s0, s0, s45
	s_add_i32 m0, s0, 0xffffff80
	ds_read_b128 v[180:183], v195 offset:49152
	ds_read_b128 v[198:201], v195 offset:50176
	ds_read_b128 v[202:205], v195 offset:51200
	ds_read_b128 v[206:209], v195 offset:52224
	ds_read_b128 v[210:213], v195 offset:53248
	ds_read_b128 v[214:217], v195 offset:54272
	ds_read_b128 v[218:221], v195 offset:55296
	ds_read_b128 v[222:225], v195 offset:56320
	global_load_lds_dwordx4 v158, s[42:43] offset:128
	s_add_i32 m0, s0, 0x1f80
	s_add_i32 s0, s67, s45
	global_load_lds_dwordx4 v162, s[42:43] offset:128
	s_add_u32 s42, s42, 0x2b0080
	s_addc_u32 s43, s43, 0
	s_mov_b32 m0, s0
	s_nop 0
	global_load_lds_dwordx4 v158, s[42:43]
	s_add_i32 m0, s0, 0x2000
	s_nop 0
	global_load_lds_dwordx4 v162, s[42:43]
	s_add_i32 m0, s55, 0xffffff80
	s_nop 0
	global_load_lds_dwordx4 v156, s[50:51] offset:128
	s_add_i32 m0, s56, 0xffffff80
	s_nop 0
	global_load_lds_dwordx4 v160, s[50:51] offset:128
	s_waitcnt vmcnt(8)
	s_waitcnt lgkmcnt(0)
	s_barrier
	s_setprio 1
	s_waitcnt lgkmcnt(0)
	v_mfma_f32_16x16x32_bf16 v[64:67], v[132:135], v[180:183], v[64:67]
	v_mfma_f32_16x16x32_bf16 v[60:63], v[140:143], v[180:183], v[60:63]
	v_mfma_f32_16x16x32_bf16 v[48:51], v[132:135], v[202:205], v[48:51]
	v_mfma_f32_16x16x32_bf16 v[44:47], v[140:143], v[202:205], v[44:47]
	v_mfma_f32_16x16x32_bf16 v[32:35], v[132:135], v[210:213], v[32:35]
	v_mfma_f32_16x16x32_bf16 v[28:31], v[140:143], v[210:213], v[28:31]
	v_mfma_f32_16x16x32_bf16 v[16:19], v[132:135], v[218:221], v[16:19]
	v_mfma_f32_16x16x32_bf16 v[12:15], v[140:143], v[218:221], v[12:15]
	v_mfma_f32_16x16x32_bf16 v[64:67], v[136:139], v[198:201], v[64:67]
	v_mfma_f32_16x16x32_bf16 v[60:63], v[144:147], v[198:201], v[60:63]
	v_mfma_f32_16x16x32_bf16 v[48:51], v[136:139], v[206:209], v[48:51]
	v_mfma_f32_16x16x32_bf16 v[44:47], v[144:147], v[206:209], v[44:47]
	v_mfma_f32_16x16x32_bf16 v[32:35], v[136:139], v[214:217], v[32:35]
	v_mfma_f32_16x16x32_bf16 v[28:31], v[144:147], v[214:217], v[28:31]
	v_mfma_f32_16x16x32_bf16 v[16:19], v[136:139], v[222:225], v[16:19]
	v_mfma_f32_16x16x32_bf16 v[12:15], v[144:147], v[222:225], v[12:15]
	s_setprio 0
	s_setprio 1
	v_mfma_f32_16x16x32_bf16 v[56:59], v[148:151], v[180:183], v[56:59]
	v_mfma_f32_16x16x32_bf16 v[52:55], v[172:175], v[180:183], v[52:55]
	v_mfma_f32_16x16x32_bf16 v[40:43], v[148:151], v[202:205], v[40:43]
	v_mfma_f32_16x16x32_bf16 v[36:39], v[172:175], v[202:205], v[36:39]
	v_mfma_f32_16x16x32_bf16 v[24:27], v[148:151], v[210:213], v[24:27]
	v_mfma_f32_16x16x32_bf16 v[20:23], v[172:175], v[210:213], v[20:23]
	v_mfma_f32_16x16x32_bf16 v[8:11], v[148:151], v[218:221], v[8:11]
	v_mfma_f32_16x16x32_bf16 v[4:7], v[172:175], v[218:221], v[4:7]
	v_mfma_f32_16x16x32_bf16 v[56:59], v[152:155], v[198:201], v[56:59]
	v_mfma_f32_16x16x32_bf16 v[52:55], v[176:179], v[198:201], v[52:55]
	v_mfma_f32_16x16x32_bf16 v[40:43], v[152:155], v[206:209], v[40:43]
	v_mfma_f32_16x16x32_bf16 v[36:39], v[176:179], v[206:209], v[36:39]
	v_mfma_f32_16x16x32_bf16 v[24:27], v[152:155], v[214:217], v[24:27]
	v_mfma_f32_16x16x32_bf16 v[20:23], v[176:179], v[214:217], v[20:23]
	v_mfma_f32_16x16x32_bf16 v[8:11], v[152:155], v[222:225], v[8:11]
	v_mfma_f32_16x16x32_bf16 v[4:7], v[176:179], v[222:225], v[4:7]
	s_setprio 0
	s_barrier
	s_add_i32 s66, s66, 2
	s_add_u32 s30, s30, 0x100
	s_addc_u32 s31, s31, 0
	s_add_u32 s64, s64, 0x100
	s_addc_u32 s65, s65, 0
	s_cmpk_gt_u32 s66, 0xa9
	s_cbranch_scc0 .LBB0_1672
	s_and_b64 vcc, exec, s[24:25]
	s_cbranch_vccz .LBB0_1675
	s_barrier

	.amdhsa_kernel _Z10fwd_kernel4Args
		.amdhsa_group_segment_fixed_size 0
		.amdhsa_private_segment_fixed_size 0
		.amdhsa_kernarg_size 496
		.amdhsa_user_sgpr_count 2
		.amdhsa_user_sgpr_dispatch_ptr 0
		.amdhsa_user_sgpr_queue_ptr 0
		.amdhsa_user_sgpr_kernarg_segment_ptr 1
		.amdhsa_user_sgpr_dispatch_id 0
		.amdhsa_user_sgpr_kernarg_preload_length 0
		.amdhsa_user_sgpr_kernarg_preload_offset 0
		.amdhsa_user_sgpr_private_segment_size 0
		.amdhsa_uses_dynamic_stack 0
		.amdhsa_enable_private_segment 0
		.amdhsa_system_sgpr_workgroup_id_x 1
		.amdhsa_system_sgpr_workgroup_id_y 0
		.amdhsa_system_sgpr_workgroup_id_z 0
		.amdhsa_system_sgpr_workgroup_info 0
		.amdhsa_system_vgpr_workitem_id 0
		.amdhsa_next_free_vgpr 255
		.amdhsa_next_free_sgpr 102
		.amdhsa_accum_offset 256
		.amdhsa_reserve_vcc 1
		.amdhsa_float_round_mode_32 0
		.amdhsa_float_round_mode_16_64 0
		.amdhsa_float_denorm_mode_32 3
		.amdhsa_float_denorm_mode_16_64 3
		.amdhsa_dx10_clamp 1
		.amdhsa_ieee_mode 1
		.amdhsa_fp16_overflow 0
		.amdhsa_tg_split 0
		.amdhsa_exception_fp_ieee_invalid_op 0
		.amdhsa_exception_fp_denorm_src 0
		.amdhsa_exception_fp_ieee_div_zero 0
		.amdhsa_exception_fp_ieee_overflow 0
		.amdhsa_exception_fp_ieee_underflow 0
		.amdhsa_exception_fp_ieee_inexact 0
		.amdhsa_exception_int_div_zero 0
	.end_amdhsa_kernel

amdhsa.kernels:
  - .agpr_count:     0
    .args:
      - .offset:         0
        .size:           240
        .value_kind:     by_value
      - .offset:         240
        .size:           4
        .value_kind:     hidden_block_count_x
      - .offset:         244
        .size:           4
        .value_kind:     hidden_block_count_y
      - .offset:         248
        .size:           4
        .value_kind:     hidden_block_count_z
      - .offset:         252
        .size:           2
        .value_kind:     hidden_group_size_x
      - .offset:         254
        .size:           2
        .value_kind:     hidden_group_size_y
      - .offset:         256
        .size:           2
        .value_kind:     hidden_group_size_z
      - .offset:         258
        .size:           2
        .value_kind:     hidden_remainder_x
      - .offset:         260
        .size:           2
        .value_kind:     hidden_remainder_y
      - .offset:         262
        .size:           2
        .value_kind:     hidden_remainder_z
      - .offset:         280
        .size:           8
        .value_kind:     hidden_global_offset_x
      - .offset:         288
        .size:           8
        .value_kind:     hidden_global_offset_y
      - .offset:         296
        .size:           8
        .value_kind:     hidden_global_offset_z
      - .offset:         304
        .size:           2
        .value_kind:     hidden_grid_dims
      - .offset:         360
        .size:           4
        .value_kind:     hidden_dynamic_lds_size
    .group_segment_fixed_size: 0
    .kernarg_segment_align: 8
    .kernarg_segment_size: 496
    .language:       OpenCL C
    .language_version:
      - 2
      - 0
    .max_flat_workgroup_size: 512
    .name:           _Z10fwd_kernel4Args
    .private_segment_fixed_size: 0
    .sgpr_count:     108
    .sgpr_spill_count: 14
    .symbol:         _Z10fwd_kernel4Args.kd
    .uniform_work_group_size: 1
    .uses_dynamic_stack: false
    .vgpr_count:     255
    .vgpr_spill_count: 0
    .wavefront_size: 64
